# NSA K/V blocks through a 4-slot LDS-DMA ring (3 blocks in flight), swizzled image; restores s46-53
# speedup vs baseline: 1.1779x; 1.0037x over previous
; DEVI int launder(int x) { asm volatile("" : "+v"(x)); return x; }
; DEVI void phase_nsa(const Params& p, unsigned char* smem) {
;   u16* sK = (u16*)smem;
;   u16* sVt = (u16*)(smem + 18432);
;   float* impH = (float*)(smem + 35840);
;   float* impT = (float*)(smem + 52736);
;   unsigned* selm = (unsigned*)(smem + 56960);
;   const float c2 = 0.125f * 1.4426950408889634f;
; #pragma unroll 1
;   for (int tile = blockIdx.x; tile < 2048; tile += gridDim.x) {
;     const int tid = launder(threadIdx.x), lane = tid & 63, w = tid >> 6, col = lane & 15, quad = lane >> 4;
;     const int tj = tile >> 5, ti = tj & 15, tk = tj >> 4;
;     const int qtile = (tk == 0) ? 63 - ti : (tk == 1) ? 32 + ti : (tk == 2) ? 31 - ti : ti;
;     const int bg = tile & 31, b = bg >> 1, g = bg & 1, q0 = qtile * 32;
;     const bool need_sel = (q0 + 31) >= 16 * 64;
;     const int h = g * 4 + w;
;     ...
;       const int lr0 = tid >> 3, lch = (tid & 7) << 3;
.LBB0_748:
	s_cmp_gt_i32 s88, 4
	s_cselect_b64 s[0:1], -1, 0
	s_cmp_lt_i32 s89, 4
	s_cselect_b64 s[2:3], -1, 0
	s_or_b64 s[0:1], s[0:1], s[2:3]
	s_and_b64 vcc, exec, s[0:1]
	s_cbranch_vccnz .LBB0_888
	v_writelane_b32 v247, s70, 42
	s_cmpk_gt_i32 s90, 0x7ff
	s_nop 0
	v_writelane_b32 v247, s71, 43
	v_writelane_b32 v247, s68, 44
	s_nop 1
	v_writelane_b32 v247, s69, 45
	v_writelane_b32 v247, s66, 46
	v_writelane_b32 v247, s90, 47
	s_cbranch_scc1 .LBB0_834
	s_load_dwordx2 s[0:1], s[68:69], 0xe8
	s_load_dwordx2 s[2:3], s[68:69], 0xf0
	s_load_dwordx2 s[4:5], s[68:69], 0x100
	s_load_dwordx2 s[6:7], s[68:69], 0x108
	s_load_dwordx2 s[8:9], s[68:69], 0x180
	s_load_dwordx2 s[10:11], s[68:69], 0x190
	s_load_dwordx2 s[12:13], s[68:69], 0x198
	s_load_dword s15, s[68:69], 0x200
	s_mov_b32 s14, s90
	v_and_b32_e32 v197, 15, v210
	v_bfe_u32 v198, v210, 4, 2
	v_and_b32_e32 v199, 63, v210
	v_xor_b32_e32 v195, 16, v199
	v_lshlrev_b32_e32 v195, 2, v195
	v_add_u32_e32 v196, 48, v199
	v_and_b32_e32 v196, 63, v196
	v_lshlrev_b32_e32 v196, 2, v196
	v_mul_u32_u24_e32 v190, 0x90, v197
	v_lshl_add_u32 v190, v198, 4, v190
	v_mul_u32_u24_e32 v191, 0x90, v197
	v_lshl_add_u32 v191, v198, 3, v191
	v_mul_u32_u24_e32 v192, 0x110, v197
	v_lshl_add_u32 v192, v198, 3, v192
	v_lshrrev_b32_e32 v211, 3, v210
	v_and_b32_e32 v212, 7, v210
	v_lshlrev_b32_e32 v212, 4, v212
	v_mul_u32_u24_e32 v193, 0x90, v211
	v_add_u32_e32 v193, v212, v193
	v_lshrrev_b32_e32 v214, 6, v210
	v_lshlrev_b32_e32 v214, 4, v214
	v_bfe_u32 v215, v210, 3, 3
	v_add_u32_e32 v214, v215, v214
	v_lshrrev_b32_e32 v215, 1, v214
	v_and_b32_e32 v215, 7, v215
	v_and_b32_e32 v216, 7, v210
	v_xor_b32_e32 v215, v216, v215
	v_lshlrev_b32_e32 v215, 4, v215
	v_mul_u32_u24_e32 v201, 0x1240, v214
	v_add_u32_e32 v201, v215, v201
	v_mul_u32_u24_e32 v203, 0x1080, v214
	v_add_u32_e32 v203, v215, v203
	v_lshrrev_b32_e32 v214, 6, v210
	v_lshlrev_b32_e32 v214, 4, v214
	v_bfe_u32 v215, v210, 3, 3
	v_add_u32_e32 v214, v215, v214
	v_add_u32_e32 v214, 8, v214
	v_lshrrev_b32_e32 v215, 1, v214
	v_and_b32_e32 v215, 7, v215
	v_and_b32_e32 v216, 7, v210
	v_xor_b32_e32 v215, v216, v215
	v_lshlrev_b32_e32 v215, 4, v215
	v_mul_u32_u24_e32 v202, 0x1240, v214
	v_add_u32_e32 v202, v215, v202
	v_mul_u32_u24_e32 v204, 0x1080, v214
	v_add_u32_e32 v204, v215, v204
	v_lshrrev_b32_e32 v211, 4, v210
	v_and_b32_e32 v212, 15, v210
	v_lshlrev_b32_e32 v212, 4, v212
	v_mul_u32_u24_e32 v194, 0x110, v211
	v_add_u32_e32 v194, v212, v194
	v_lshrrev_b32_e32 v209, 6, v210
	v_mul_u32_u24_e32 v205, 0x1240, v197
	v_lshl_add_u32 v205, v209, 7, v205
	v_lshl_add_u32 v205, v198, 4, v205
	v_add_u32_e32 v206, 0x12400, v205
	v_mov_b32_e32 v200, 0x3e38aa3b
	s_waitcnt lgkmcnt(0)
	s_cmp_ge_u32 s14, 0x800
	s_cbranch_scc1 .Lp4_done

; DEVI void phase_nsa(const Params& p, unsigned char* smem) {
;     ...
;     unsigned sm[2] = {selm[col], selm[16 + col]};
;     unsigned uni = 0u;
; #pragma unroll
;     for (int i = 0; i < 32; ++i) uni |= selm[i];
;     const int kbmax = (q0 + 31) >> 6;
;     {
;       float m[2] = {-1e30f, -1e30f}, l[2] = {0.f, 0.f};
;       f32x4 o[2][4];
; #pragma unroll
;       for (int qt = 0; qt < 2; ++qt)
; #pragma unroll
;         for (int dt = 0; dt < 4; ++dt) o[qt][dt] = f32x4{0.f, 0.f, 0.f, 0.f};
;       unsigned rem = (kbmax >= 31) ? uni : (uni & ((1u << (kbmax + 1)) - 1u));
;       int kb = rem ? (__ffs((int)rem) - 1) : -1;
;       uint4 rk0, rk1, rv0, rv1;
;       const int lr0 = tid >> 3, lch = (tid & 7) << 3;
;     ...
;       if (kb >= 0) { LOADKV_(kb, C_KS, p.vts) }
.Lp4_selend:
	s_waitcnt lgkmcnt(0)
	s_barrier
	v_lshlrev_b32_e32 v231, 2, v197
	ds_read_b32 v188, v231 offset:56960
	ds_read_b32 v189, v231 offset:57024
	v_lshlrev_b32_e32 v232, 2, v199
	v_and_b32_e32 v232, 0x7c, v232
	ds_read_b32 v232, v232 offset:56960
	s_waitcnt lgkmcnt(0)
	s_nop 0
	v_readlane_b32 s28, v232, 0
	s_mov_b32 s29, s28
	v_readlane_b32 s22, v232, 1
	s_or_b32 s28, s28, s22
	s_and_b32 s29, s29, s22
	v_readlane_b32 s22, v232, 2
	s_or_b32 s28, s28, s22
	s_and_b32 s29, s29, s22
	v_readlane_b32 s22, v232, 3
	s_or_b32 s28, s28, s22
	s_and_b32 s29, s29, s22
	v_readlane_b32 s22, v232, 4
	s_or_b32 s28, s28, s22
	s_and_b32 s29, s29, s22
	v_readlane_b32 s22, v232, 5
	s_or_b32 s28, s28, s22
	s_and_b32 s29, s29, s22
	v_readlane_b32 s22, v232, 6
	s_or_b32 s28, s28, s22
	s_and_b32 s29, s29, s22
	v_readlane_b32 s22, v232, 7
	s_or_b32 s28, s28, s22
	s_and_b32 s29, s29, s22
	v_readlane_b32 s22, v232, 8
	s_or_b32 s28, s28, s22
	s_and_b32 s29, s29, s22
	v_readlane_b32 s22, v232, 9
	s_or_b32 s28, s28, s22
	s_and_b32 s29, s29, s22
	v_readlane_b32 s22, v232, 10
	s_or_b32 s28, s28, s22
	s_and_b32 s29, s29, s22
	v_readlane_b32 s22, v232, 11
	s_or_b32 s28, s28, s22
	s_and_b32 s29, s29, s22
	v_readlane_b32 s22, v232, 12
	s_or_b32 s28, s28, s22
	s_and_b32 s29, s29, s22
	v_readlane_b32 s22, v232, 13
	s_or_b32 s28, s28, s22
	s_and_b32 s29, s29, s22
	v_readlane_b32 s22, v232, 14
	s_or_b32 s28, s28, s22
	s_and_b32 s29, s29, s22
	v_readlane_b32 s22, v232, 15
	s_or_b32 s28, s28, s22
	s_and_b32 s29, s29, s22
	v_readlane_b32 s22, v232, 16
	s_or_b32 s28, s28, s22
	s_and_b32 s29, s29, s22
	v_readlane_b32 s22, v232, 17
	s_or_b32 s28, s28, s22
	s_and_b32 s29, s29, s22
	v_readlane_b32 s22, v232, 18
	s_or_b32 s28, s28, s22
	s_and_b32 s29, s29, s22
	v_readlane_b32 s22, v232, 19
	s_or_b32 s28, s28, s22
	s_and_b32 s29, s29, s22
	v_readlane_b32 s22, v232, 20
	s_or_b32 s28, s28, s22
	s_and_b32 s29, s29, s22
	v_readlane_b32 s22, v232, 21
	s_or_b32 s28, s28, s22
	s_and_b32 s29, s29, s22
	v_readlane_b32 s22, v232, 22
	s_or_b32 s28, s28, s22
	s_and_b32 s29, s29, s22
	v_readlane_b32 s22, v232, 23
	s_or_b32 s28, s28, s22
	s_and_b32 s29, s29, s22
	v_readlane_b32 s22, v232, 24
	s_or_b32 s28, s28, s22
	s_and_b32 s29, s29, s22
	v_readlane_b32 s22, v232, 25
	s_or_b32 s28, s28, s22
	s_and_b32 s29, s29, s22
	v_readlane_b32 s22, v232, 26
	s_or_b32 s28, s28, s22
	s_and_b32 s29, s29, s22
	v_readlane_b32 s22, v232, 27
	s_or_b32 s28, s28, s22
	s_and_b32 s29, s29, s22
	v_readlane_b32 s22, v232, 28
	s_or_b32 s28, s28, s22
	s_and_b32 s29, s29, s22
	v_readlane_b32 s22, v232, 29
	s_or_b32 s28, s28, s22
	s_and_b32 s29, s29, s22
	v_readlane_b32 s22, v232, 30
	s_or_b32 s28, s28, s22
	s_and_b32 s29, s29, s22
	v_readlane_b32 s22, v232, 31
	s_or_b32 s28, s28, s22
	s_and_b32 s29, s29, s22
	v_lshrrev_b32_e32 v241, 1, v197
	v_and_b32_e32 v241, 7, v241
	v_add_u32_e32 v242, 0, v198
	v_xor_b32_e32 v242, v241, v242
	v_lshlrev_b32_e32 v242, 4, v242
	v_lshl_add_u32 v235, v197, 7, v242
	v_add_u32_e32 v242, 4, v198
	v_xor_b32_e32 v242, v241, v242
	v_lshlrev_b32_e32 v242, 4, v242
	v_lshl_add_u32 v236, v197, 7, v242
	v_lshrrev_b32_e32 v242, 1, v198
	v_add_u32_e32 v242, 0, v242
	v_xor_b32_e32 v242, v241, v242
	v_lshlrev_b32_e32 v242, 4, v242
	v_lshl_add_u32 v237, v197, 7, v242
	v_and_b32_e32 v242, 1, v198
	v_lshl_add_u32 v237, v242, 3, v237
	v_add_u32_e32 v237, 0x2000, v237
	v_xor_b32_e32 v239, 32, v237
	v_lshrrev_b32_e32 v242, 1, v198
	v_add_u32_e32 v242, 4, v242
	v_xor_b32_e32 v242, v241, v242
	v_lshlrev_b32_e32 v242, 4, v242
	v_lshl_add_u32 v238, v197, 7, v242
	v_and_b32_e32 v242, 1, v198
	v_lshl_add_u32 v238, v242, 3, v238
	v_add_u32_e32 v238, 0x2000, v238
	v_xor_b32_e32 v240, 32, v238
	s_nop 0
	v_readfirstlane_b32 s50, v209
	s_lshl_b32 s50, s50, 11
	s_mov_b32 s42, s4
	s_mov_b32 s43, s5
	s_lshl_b32 s31, s17, 7
	s_add_u32 s31, s31, 3584
	s_mov_b32 s41, 0x7fffffff
	v_mov_b32_e32 v16, 0
	v_mov_b32_e32 v17, 0
	v_mov_b32_e32 v18, 0
	v_mov_b32_e32 v19, 0
	v_mov_b32_e32 v20, 0
	v_mov_b32_e32 v21, 0
	v_mov_b32_e32 v22, 0
	v_mov_b32_e32 v23, 0
	v_mov_b32_e32 v24, 0
	v_mov_b32_e32 v25, 0
	v_mov_b32_e32 v26, 0
	v_mov_b32_e32 v27, 0
	v_mov_b32_e32 v28, 0
	v_mov_b32_e32 v29, 0
	v_mov_b32_e32 v30, 0
	v_mov_b32_e32 v31, 0
	v_mov_b32_e32 v32, 0
	v_mov_b32_e32 v33, 0
	v_mov_b32_e32 v34, 0
	v_mov_b32_e32 v35, 0
	v_mov_b32_e32 v36, 0
	v_mov_b32_e32 v37, 0
	v_mov_b32_e32 v38, 0
	v_mov_b32_e32 v39, 0
	v_mov_b32_e32 v40, 0
	v_mov_b32_e32 v41, 0
	v_mov_b32_e32 v42, 0
	v_mov_b32_e32 v43, 0
	v_mov_b32_e32 v44, 0
	v_mov_b32_e32 v45, 0
	v_mov_b32_e32 v46, 0
	v_mov_b32_e32 v47, 0
	v_mov_b32_e32 v182, 0xf149f2ca
	v_mov_b32_e32 v184, 0
	v_mov_b32_e32 v183, 0xf149f2ca
	v_mov_b32_e32 v185, 0
	s_add_u32 s22, s20, 1
	s_lshl_b32 s22, 1, s22
	s_sub_u32 s22, s22, 1
	s_cmp_ge_u32 s20, 31
	s_cselect_b32 s22, -1, s22
	s_and_b32 s25, s28, s22
	s_ff1_i32_b32 s26, s25
	s_add_u32 s22, s25, -1
	s_and_b32 s25, s25, s22
	s_ff1_i32_b32 s47, s25
	s_add_u32 s22, s25, -1
	s_and_b32 s25, s25, s22
	s_ff1_i32_b32 s48, s25
	s_add_u32 s22, s25, -1
	s_and_b32 s25, s25, s22
	s_ff1_i32_b32 s49, s25
	s_add_u32 s22, s25, -1
	s_and_b32 s25, s25, s22
	s_cmp_lt_i32 s26, 0
	s_cbranch_scc1 .Lp4_sel_end
; DEVI void phase_nsa(const Params& p, unsigned char* smem) {
;     ...
;       if (kb >= 0) { LOADKV_(kb, C_KS, p.vts) }
; #pragma unroll 1
;       while (kb >= 0) {
;         rem &= rem - 1u;
;         const int nkb = rem ? (__ffs((int)rem) - 1) : -1;
;         __syncthreads();
;         STOREKV_()
;         if (nkb >= 0) { LOADKV_(nkb, C_KS, p.vts) }
;         __syncthreads();
	s_mov_b32 s46, 0
	s_lshl_b32 s22, s16, 11
	s_lshl_b32 s23, s26, 6
	s_add_u32 s22, s22, s23
	s_mul_i32 s22, s22, 0x1240
	s_add_u32 s22, s22, s31
	s_mul_i32 s23, s18, 0x42000
	s_lshl_b32 s24, s26, 7
	s_add_u32 s23, s23, s24
	s_add_u32 s51, s46, s50
	s_mov_b32 m0, s51
	v_add_u32_e32 v211, s22, v201
	v_mov_b32_e32 v245, s1
	v_add_co_u32_e32 v244, vcc, s0, v211
	s_nop 1
	v_addc_co_u32_e32 v245, vcc, 0, v245, vcc
	global_load_lds_dwordx4 v[244:245], off
	s_add_u32 s51, s51, 1024
	s_mov_b32 m0, s51
	v_add_u32_e32 v212, s22, v202
	v_mov_b32_e32 v245, s1
	v_add_co_u32_e32 v244, vcc, s0, v212
	s_nop 1
	v_addc_co_u32_e32 v245, vcc, 0, v245, vcc
	global_load_lds_dwordx4 v[244:245], off
	s_add_u32 s51, s51, 7168
	s_mov_b32 m0, s51
	v_add_u32_e32 v213, s23, v203
	v_mov_b32_e32 v245, s43
	v_add_co_u32_e32 v244, vcc, s42, v213
	s_nop 1
	v_addc_co_u32_e32 v245, vcc, 0, v245, vcc
	global_load_lds_dwordx4 v[244:245], off
	s_add_u32 s51, s51, 1024
	s_mov_b32 m0, s51
	v_add_u32_e32 v214, s23, v204
	v_mov_b32_e32 v245, s43
	v_add_co_u32_e32 v244, vcc, s42, v214
	s_nop 1
	v_addc_co_u32_e32 v245, vcc, 0, v245, vcc
	global_load_lds_dwordx4 v[244:245], off
	s_movk_i32 s53, 0x4000
	s_cmp_lt_i32 s47, 0
	s_cbranch_scc1 .Lp4_sel_pq1
	s_lshl_b32 s22, s16, 11
	s_lshl_b32 s23, s47, 6
	s_add_u32 s22, s22, s23
	s_mul_i32 s22, s22, 0x1240
	s_add_u32 s22, s22, s31
	s_mul_i32 s23, s18, 0x42000
	s_lshl_b32 s24, s47, 7
	s_add_u32 s23, s23, s24
	s_add_u32 s51, s53, s50
	s_mov_b32 m0, s51
	v_add_u32_e32 v211, s22, v201
	v_mov_b32_e32 v245, s1
	v_add_co_u32_e32 v244, vcc, s0, v211
	s_nop 1
	v_addc_co_u32_e32 v245, vcc, 0, v245, vcc
	global_load_lds_dwordx4 v[244:245], off
	s_add_u32 s51, s51, 1024
	s_mov_b32 m0, s51
	v_add_u32_e32 v212, s22, v202
	v_mov_b32_e32 v245, s1
	v_add_co_u32_e32 v244, vcc, s0, v212
	s_nop 1
	v_addc_co_u32_e32 v245, vcc, 0, v245, vcc
	global_load_lds_dwordx4 v[244:245], off
	s_add_u32 s51, s51, 7168
	s_mov_b32 m0, s51
	v_add_u32_e32 v213, s23, v203
	v_mov_b32_e32 v245, s43
	v_add_co_u32_e32 v244, vcc, s42, v213
	s_nop 1
	v_addc_co_u32_e32 v245, vcc, 0, v245, vcc
	global_load_lds_dwordx4 v[244:245], off
	s_add_u32 s51, s51, 1024
	s_mov_b32 m0, s51
	v_add_u32_e32 v214, s23, v204
	v_mov_b32_e32 v245, s43
	v_add_co_u32_e32 v244, vcc, s42, v214
	s_nop 1
	v_addc_co_u32_e32 v245, vcc, 0, v245, vcc
	global_load_lds_dwordx4 v[244:245], off
.Lp4_sel_pq1:
	s_mov_b32 s53, 0x8000
	s_cmp_lt_i32 s48, 0
	s_cbranch_scc1 .Lp4_sel_pq2
	s_lshl_b32 s22, s16, 11
	s_lshl_b32 s23, s48, 6
	s_add_u32 s22, s22, s23
	s_mul_i32 s22, s22, 0x1240
	s_add_u32 s22, s22, s31
	s_mul_i32 s23, s18, 0x42000
	s_lshl_b32 s24, s48, 7
	s_add_u32 s23, s23, s24
	s_add_u32 s51, s53, s50
	s_mov_b32 m0, s51
	v_add_u32_e32 v211, s22, v201
	v_mov_b32_e32 v245, s1
	v_add_co_u32_e32 v244, vcc, s0, v211
	s_nop 1
	v_addc_co_u32_e32 v245, vcc, 0, v245, vcc
	global_load_lds_dwordx4 v[244:245], off
	s_add_u32 s51, s51, 1024
	s_mov_b32 m0, s51
	v_add_u32_e32 v212, s22, v202
	v_mov_b32_e32 v245, s1
	v_add_co_u32_e32 v244, vcc, s0, v212
	s_nop 1
	v_addc_co_u32_e32 v245, vcc, 0, v245, vcc
	global_load_lds_dwordx4 v[244:245], off
	s_add_u32 s51, s51, 7168
	s_mov_b32 m0, s51
	v_add_u32_e32 v213, s23, v203
	v_mov_b32_e32 v245, s43
	v_add_co_u32_e32 v244, vcc, s42, v213
	s_nop 1
	v_addc_co_u32_e32 v245, vcc, 0, v245, vcc
	global_load_lds_dwordx4 v[244:245], off
	s_add_u32 s51, s51, 1024
	s_mov_b32 m0, s51
	v_add_u32_e32 v214, s23, v204
	v_mov_b32_e32 v245, s43
	v_add_co_u32_e32 v244, vcc, s42, v214
	s_nop 1
	v_addc_co_u32_e32 v245, vcc, 0, v245, vcc
	global_load_lds_dwordx4 v[244:245], off
.Lp4_sel_pq2:
.Lp4_sel_loop:
	s_cmp_lt_i32 s48, 0
	s_cbranch_scc1 .Lp4_sel_w1
	s_waitcnt vmcnt(8)
	s_branch .Lp4_sel_w0
.Lp4_sel_w1:
	s_cmp_lt_i32 s47, 0
	s_cbranch_scc1 .Lp4_sel_w2
	s_waitcnt vmcnt(4)
	s_branch .Lp4_sel_w0

; DEVI f32x4 mfma16(bf16x8 a, bf16x8 b, f32x4 c) { return __builtin_amdgcn_mfma_f32_16x16x32_bf16(a, b, c, 0, 0, 0); }
; template <int DH, int NQ, int LDK, class MaskF>
; DEVI void attn_qk(const u16* sK, const bf16x8 (&qf)[NQ][DH / 32], f32x4 (&o)[NQ][DH / 16], float (&m)[NQ], float (&l)[NQ],
;                   float c2, int lane, MaskF valid, bf16x8 (&pb)[NQ][2]) {
;   const int col = lane & 15, quad = lane >> 4;
;   f32x4 s[NQ][4];
;   __builtin_amdgcn_s_setprio(1);
; #pragma unroll
;   for (int kt = 0; kt < 4; ++kt) {
; #pragma unroll
;     for (int qt = 0; qt < NQ; ++qt) s[qt][kt] = f32x4{0.f, 0.f, 0.f, 0.f};
; #pragma unroll
;     for (int ks = 0; ks < DH / 32; ++ks) {
;       const bf16x8 kf = *(const bf16x8*)(sK + (16 * kt + col) * LDK + 32 * ks + 8 * quad);
; #pragma unroll
;       for (int qt = 0; qt < NQ; ++qt) s[qt][kt] = mfma16(kf, qf[qt][ks], s[qt][kt]);
;     }
;   }
;   __builtin_amdgcn_s_setprio(0);
; DEVI void phase_nsa(const Params& p, unsigned char* smem) {
;     ...
;       if (kb >= 0) { LOADKV_(kb, C_KS, p.vts) }
; #pragma unroll 1
;       while (kb >= 0) {
;         rem &= rem - 1u;
;         const int nkb = rem ? (__ffs((int)rem) - 1) : -1;
;         __syncthreads();
;         STOREKV_()
;         if (nkb >= 0) { LOADKV_(nkb, C_KS, p.vts) }
;         __syncthreads();
;         const int lim0 = ((sm[0] >> kb) & 1u) ? tq[0] : -1, lim1 = ((sm[1] >> kb) & 1u) ? tq[1] : -1;
;         attn_tile<64, 2, 72, 72>(sK, sVt, qf, o, m, l, c2, lane, [&](int qt, int kl) {
;           return (kb * 64 + kl) <= (qt ? lim1 : lim0);
;         });
.Lp4_sel_w0:
	s_barrier
	s_add_u32 s53, s46, 0xc000
	s_and_b32 s53, s53, 0xffff
	s_cmp_lt_i32 s49, 0
	s_cbranch_scc1 .Lp4_sel_nq3
	s_lshl_b32 s22, s16, 11
	s_lshl_b32 s23, s49, 6
	s_add_u32 s22, s22, s23
	s_mul_i32 s22, s22, 0x1240
	s_add_u32 s22, s22, s31
	s_mul_i32 s23, s18, 0x42000
	s_lshl_b32 s24, s49, 7
	s_add_u32 s23, s23, s24
	s_add_u32 s51, s53, s50
	s_mov_b32 m0, s51
	v_add_u32_e32 v211, s22, v201
	v_mov_b32_e32 v245, s1
	v_add_co_u32_e32 v244, vcc, s0, v211
	s_nop 1
	v_addc_co_u32_e32 v245, vcc, 0, v245, vcc
	global_load_lds_dwordx4 v[244:245], off
	s_add_u32 s51, s51, 1024
	s_mov_b32 m0, s51
	v_add_u32_e32 v212, s22, v202
	v_mov_b32_e32 v245, s1
	v_add_co_u32_e32 v244, vcc, s0, v212
	s_nop 1
	v_addc_co_u32_e32 v245, vcc, 0, v245, vcc
	global_load_lds_dwordx4 v[244:245], off
	s_add_u32 s51, s51, 7168
	s_mov_b32 m0, s51
	v_add_u32_e32 v213, s23, v203
	v_mov_b32_e32 v245, s43
	v_add_co_u32_e32 v244, vcc, s42, v213
	s_nop 1
	v_addc_co_u32_e32 v245, vcc, 0, v245, vcc
	global_load_lds_dwordx4 v[244:245], off
	s_add_u32 s51, s51, 1024
	s_mov_b32 m0, s51
	v_add_u32_e32 v214, s23, v204
	v_mov_b32_e32 v245, s43
	v_add_co_u32_e32 v244, vcc, s42, v214
	s_nop 1
	v_addc_co_u32_e32 v245, vcc, 0, v245, vcc
	global_load_lds_dwordx4 v[244:245], off
.Lp4_sel_nq3:
	s_lshl_b32 s30, s26, 6
	v_lshrrev_b32_e32 v215, s26, v188
	v_and_b32_e32 v215, 1, v215
	v_cmp_eq_u32_e64 s[32:33], 1, v215
	v_mov_b32_e32 v216, -1
	v_lshlrev_b32_e32 v217, 2, v198
	v_cndmask_b32_e64 v207, v216, v186, s[32:33]
	v_sub_u32_e32 v207, v207, v217
	v_lshrrev_b32_e32 v215, s26, v189
	v_and_b32_e32 v215, 1, v215
	v_cmp_eq_u32_e64 s[32:33], 1, v215
	v_mov_b32_e32 v216, -1
	v_lshlrev_b32_e32 v217, 2, v198
	v_cndmask_b32_e64 v208, v216, v187, s[32:33]
	v_sub_u32_e32 v208, v208, v217
	s_lshr_b32 s22, s29, s26
	s_and_b32 s22, s22, 1
	s_add_u32 s23, s30, 63
	s_cmp_le_u32 s23, s19
	s_cselect_b32 s24, s22, 0
	s_cmp_eq_u32 s24, 0
	s_cbranch_scc1 .Lp4_sel_masked
	v_add_u32_e32 v227, s46, v235
	v_add_u32_e32 v228, s46, v236
	v_add_u32_e32 v231, s46, v237
	v_add_u32_e32 v233, s46, v239
	v_add_u32_e32 v232, s46, v238
	v_add_u32_e32 v234, s46, v240
	ds_read_b128 v[112:115], v227
	ds_read_b128 v[116:119], v228
	ds_read_b128 v[120:123], v227 offset:2048
	ds_read_b128 v[124:127], v228 offset:2048
	ds_read_b128 v[128:131], v227 offset:4096
	ds_read_b128 v[132:135], v228 offset:4096
	ds_read_b128 v[136:139], v227 offset:6144
	ds_read_b128 v[140:143], v228 offset:6144
	s_waitcnt lgkmcnt(7)
	v_mfma_f32_16x16x32_bf16 v[80:83], v[112:115], v[0:3], 0
	v_mfma_f32_16x16x32_bf16 v[96:99], v[112:115], v[8:11], 0
	s_waitcnt lgkmcnt(6)
	v_mfma_f32_16x16x32_bf16 v[80:83], v[116:119], v[4:7], v[80:83]
	v_mfma_f32_16x16x32_bf16 v[96:99], v[116:119], v[12:15], v[96:99]
	s_waitcnt lgkmcnt(5)
	v_mfma_f32_16x16x32_bf16 v[84:87], v[120:123], v[0:3], 0
	v_mfma_f32_16x16x32_bf16 v[100:103], v[120:123], v[8:11], 0
	s_waitcnt lgkmcnt(4)
	v_mfma_f32_16x16x32_bf16 v[84:87], v[124:127], v[4:7], v[84:87]
	v_mfma_f32_16x16x32_bf16 v[100:103], v[124:127], v[12:15], v[100:103]
	s_waitcnt lgkmcnt(3)
	v_mfma_f32_16x16x32_bf16 v[88:91], v[128:131], v[0:3], 0
	v_mfma_f32_16x16x32_bf16 v[104:107], v[128:131], v[8:11], 0
	s_waitcnt lgkmcnt(2)
	v_mfma_f32_16x16x32_bf16 v[88:91], v[132:135], v[4:7], v[88:91]
	v_mfma_f32_16x16x32_bf16 v[104:107], v[132:135], v[12:15], v[104:107]
	s_waitcnt lgkmcnt(1)
	v_mfma_f32_16x16x32_bf16 v[92:95], v[136:139], v[0:3], 0
	v_mfma_f32_16x16x32_bf16 v[108:111], v[136:139], v[8:11], 0
	s_waitcnt lgkmcnt(0)
	v_mfma_f32_16x16x32_bf16 v[92:95], v[140:143], v[4:7], v[92:95]
	v_mfma_f32_16x16x32_bf16 v[108:111], v[140:143], v[12:15], v[108:111]
	ds_read_b64 v[112:113], v231 offset:0
	ds_read_b64 v[114:115], v233 offset:0
	ds_read_b64 v[116:117], v232 offset:0
	ds_read_b64 v[118:119], v234 offset:0
	ds_read_b64 v[120:121], v231 offset:2048
	ds_read_b64 v[122:123], v233 offset:2048
	ds_read_b64 v[124:125], v232 offset:2048
	ds_read_b64 v[126:127], v234 offset:2048
	s_nop 3
	v_max3_f32 v215, v80, v81, v82
	v_max3_f32 v215, v215, v83, v84
	v_max3_f32 v215, v215, v85, v86
	v_max3_f32 v215, v215, v87, v88
	v_max3_f32 v215, v215, v89, v90
	v_max3_f32 v215, v215, v91, v92
	v_max3_f32 v215, v215, v93, v94
	v_max_f32_e32 v215, v95, v215
	ds_bpermute_b32 v216, v195, v215
	s_waitcnt lgkmcnt(0)
; template <int DH, int NQ, int LDK, class MaskF>
; DEVI void attn_qk(const u16* sK, const bf16x8 (&qf)[NQ][DH / 32], f32x4 (&o)[NQ][DH / 16], float (&m)[NQ], float (&l)[NQ],
;                   float c2, int lane, MaskF valid, bf16x8 (&pb)[NQ][2]) {
;     ...
; #pragma unroll
;   for (int qt = 0; qt < NQ; ++qt) {
;     float mx = -1e30f;
; #pragma unroll
;     for (int kt = 0; kt < 4; ++kt)
; #pragma unroll
;       for (int r = 0; r < 4; ++r) {
;         const bool v = valid(qt, 16 * kt + 4 * quad + r);
;         const float sv = v ? s[qt][kt][r] : -1e30f;
;         s[qt][kt][r] = sv;
;         mx = fmaxf(mx, sv);
;       }
;     mx = fmaxf(mx, __shfl_xor(mx, 16));
;     mx = fmaxf(mx, __shfl_xor(mx, 32));
;     const float mn = fmaxf(m[qt], mx);
;     const float alpha = fexp2((m[qt] - mn) * c2);
;     m[qt] = mn;
;     const float mc = fmaxf(mn, -1e20f) * c2;
;     float ps = 0.f;
; #pragma unroll
;     for (int kt = 0; kt < 4; ++kt)
; #pragma unroll
;       for (int r = 0; r < 4; ++r) {
;         const float pv = fexp2(__builtin_fmaf(s[qt][kt][r], c2, -mc));
;         ps += pv;
;         s[qt][kt][r] = pv;
;       }
;     l[qt] = l[qt] * alpha + ps;
; #pragma unroll
;     for (int dt = 0; dt < DH / 16; ++dt) o[qt][dt] *= alpha;
; #pragma unroll
;     for (int kk = 0; kk < 2; ++kk) {
;       union { bf16x8 v; unsigned u[4]; } cv;
;       cv.u[0] = pack2(s[qt][2 * kk][0], s[qt][2 * kk][1]);
;       cv.u[1] = pack2(s[qt][2 * kk][2], s[qt][2 * kk][3]);
;       cv.u[2] = pack2(s[qt][2 * kk + 1][0], s[qt][2 * kk + 1][1]);
;       cv.u[3] = pack2(s[qt][2 * kk + 1][2], s[qt][2 * kk + 1][3]);
;       pb[qt][kk] = cv.v;
;     }
;   }
; }
; template <int DH, int NQ, int LDV>
; DEVI void attn_pv(const u16* sVt, const bf16x8 (&pb)[NQ][2], f32x4 (&o)[NQ][DH / 16], int lane) {
;   const int col = lane & 15, quad = lane >> 4;
;   __builtin_amdgcn_s_setprio(1);
; #pragma unroll
;   for (int dt = 0; dt < DH / 16; ++dt) {
; #pragma unroll
;     for (int kk = 0; kk < 2; ++kk) {
;       union { bf16x8 v; uint2 h[2]; } cv;
;       cv.h[0] = *(const uint2*)(sVt + (16 * dt + col) * LDV + 32 * kk + 4 * quad);
;       cv.h[1] = *(const uint2*)(sVt + (16 * dt + col) * LDV + 32 * kk + 16 + 4 * quad);
; #pragma unroll
;       for (int qt = 0; qt < NQ; ++qt) o[qt][dt] = mfma16(cv.v, pb[qt][kk], o[qt][dt]);
;     }
;   }
;   __builtin_amdgcn_s_setprio(0);
	v_max_f32_e32 v215, v216, v215
	v_mov_b32_e32 v216, v215
	v_mov_b32_e32 v217, v215
	s_nop 1
	v_permlane32_swap_b32_e32 v216, v217
	v_max_f32_e32 v215, v216, v217
	v_max_f32_e32 v218, v182, v215
	v_sub_f32_e32 v219, v182, v218
	v_mul_f32_e32 v219, v200, v219
	v_exp_f32_e32 v219, v219
	v_mov_b32_e32 v182, v218
	v_max_f32_e32 v220, 0xe0ad78ec, v218
	v_mul_f32_e32 v220, 0xbe38aa3b, v220
	v_fma_f32 v80, v80, v200, v220
	v_exp_f32_e32 v80, v80
	v_fma_f32 v81, v81, v200, v220
	v_exp_f32_e32 v81, v81
	v_fma_f32 v82, v82, v200, v220
	v_exp_f32_e32 v82, v82
	v_fma_f32 v83, v83, v200, v220
	v_exp_f32_e32 v83, v83
	v_fma_f32 v84, v84, v200, v220
	v_exp_f32_e32 v84, v84
	v_fma_f32 v85, v85, v200, v220
	v_exp_f32_e32 v85, v85
	v_fma_f32 v86, v86, v200, v220
	v_exp_f32_e32 v86, v86
	v_fma_f32 v87, v87, v200, v220
	v_exp_f32_e32 v87, v87
	v_fma_f32 v88, v88, v200, v220
	v_exp_f32_e32 v88, v88
	v_fma_f32 v89, v89, v200, v220
	v_exp_f32_e32 v89, v89
	v_fma_f32 v90, v90, v200, v220
	v_exp_f32_e32 v90, v90
	v_fma_f32 v91, v91, v200, v220
	v_exp_f32_e32 v91, v91
	v_fma_f32 v92, v92, v200, v220
	v_exp_f32_e32 v92, v92
	v_fma_f32 v93, v93, v200, v220
	v_exp_f32_e32 v93, v93
	v_fma_f32 v94, v94, v200, v220
	v_exp_f32_e32 v94, v94
	v_fma_f32 v95, v95, v200, v220
	v_exp_f32_e32 v95, v95
	s_nop 0
	v_add_f32_e32 v221, v80, v81
	v_add_f32_e32 v221, v82, v221
	v_add_f32_e32 v221, v83, v221
	v_add_f32_e32 v221, v84, v221
	v_add_f32_e32 v221, v85, v221
	v_add_f32_e32 v221, v86, v221
	v_add_f32_e32 v221, v87, v221
	v_add_f32_e32 v221, v88, v221
	v_add_f32_e32 v221, v89, v221
	v_add_f32_e32 v221, v90, v221
	v_add_f32_e32 v221, v91, v221
	v_add_f32_e32 v221, v92, v221
	v_add_f32_e32 v221, v93, v221
	v_add_f32_e32 v221, v94, v221
	v_add_f32_e32 v221, v95, v221
	v_fma_f32 v184, v184, v219, v221
	v_mul_f32_e32 v16, v219, v16
	v_mul_f32_e32 v17, v219, v17
	v_mul_f32_e32 v18, v219, v18
	v_mul_f32_e32 v19, v219, v19
	v_mul_f32_e32 v20, v219, v20
	v_mul_f32_e32 v21, v219, v21
	v_mul_f32_e32 v22, v219, v22
	v_mul_f32_e32 v23, v219, v23
	v_mul_f32_e32 v24, v219, v24
	v_mul_f32_e32 v25, v219, v25
	v_mul_f32_e32 v26, v219, v26
	v_mul_f32_e32 v27, v219, v27
	v_mul_f32_e32 v28, v219, v28
	v_mul_f32_e32 v29, v219, v29
	v_mul_f32_e32 v30, v219, v30
	v_mul_f32_e32 v31, v219, v31
	v_cvt_pk_bf16_f32 v144, v80, v81
	v_cvt_pk_bf16_f32 v145, v82, v83
	v_cvt_pk_bf16_f32 v146, v84, v85
	v_cvt_pk_bf16_f32 v147, v86, v87
	v_cvt_pk_bf16_f32 v148, v88, v89
	v_cvt_pk_bf16_f32 v149, v90, v91
	v_cvt_pk_bf16_f32 v150, v92, v93
	v_cvt_pk_bf16_f32 v151, v94, v95
	v_max3_f32 v215, v96, v97, v98
	v_max3_f32 v215, v215, v99, v100
	v_max3_f32 v215, v215, v101, v102
	v_max3_f32 v215, v215, v103, v104
	v_max3_f32 v215, v215, v105, v106
	v_max3_f32 v215, v215, v107, v108
	v_max3_f32 v215, v215, v109, v110
	v_max_f32_e32 v215, v111, v215
	ds_bpermute_b32 v216, v195, v215
	s_waitcnt lgkmcnt(0)
	v_max_f32_e32 v215, v216, v215
	v_mov_b32_e32 v216, v215
	v_mov_b32_e32 v217, v215
	s_nop 1
	v_permlane32_swap_b32_e32 v216, v217
	v_max_f32_e32 v215, v216, v217
	v_max_f32_e32 v218, v183, v215
	v_sub_f32_e32 v219, v183, v218
	v_mul_f32_e32 v219, v200, v219
	v_exp_f32_e32 v219, v219
	v_mov_b32_e32 v183, v218
	v_max_f32_e32 v220, 0xe0ad78ec, v218
	v_mul_f32_e32 v220, 0xbe38aa3b, v220
	v_fma_f32 v96, v96, v200, v220
	v_exp_f32_e32 v96, v96
	v_fma_f32 v97, v97, v200, v220
	v_exp_f32_e32 v97, v97
	v_fma_f32 v98, v98, v200, v220
	v_exp_f32_e32 v98, v98
	v_fma_f32 v99, v99, v200, v220
	v_exp_f32_e32 v99, v99
	v_fma_f32 v100, v100, v200, v220
	v_exp_f32_e32 v100, v100
	v_fma_f32 v101, v101, v200, v220
	v_exp_f32_e32 v101, v101
	v_fma_f32 v102, v102, v200, v220
	v_exp_f32_e32 v102, v102
	v_fma_f32 v103, v103, v200, v220
	v_exp_f32_e32 v103, v103
	v_fma_f32 v104, v104, v200, v220
	v_exp_f32_e32 v104, v104
	v_fma_f32 v105, v105, v200, v220
	v_exp_f32_e32 v105, v105
	v_fma_f32 v106, v106, v200, v220
	v_exp_f32_e32 v106, v106
	v_fma_f32 v107, v107, v200, v220
	v_exp_f32_e32 v107, v107
	v_fma_f32 v108, v108, v200, v220
	v_exp_f32_e32 v108, v108
	v_fma_f32 v109, v109, v200, v220
	v_exp_f32_e32 v109, v109
	v_fma_f32 v110, v110, v200, v220
	v_exp_f32_e32 v110, v110
	v_fma_f32 v111, v111, v200, v220
	v_exp_f32_e32 v111, v111
	s_nop 0
	v_add_f32_e32 v221, v96, v97
	v_add_f32_e32 v221, v98, v221
	v_add_f32_e32 v221, v99, v221
	v_add_f32_e32 v221, v100, v221
	v_add_f32_e32 v221, v101, v221
	v_add_f32_e32 v221, v102, v221
	v_add_f32_e32 v221, v103, v221
	v_add_f32_e32 v221, v104, v221
	v_add_f32_e32 v221, v105, v221
	v_add_f32_e32 v221, v106, v221
	v_add_f32_e32 v221, v107, v221
	v_add_f32_e32 v221, v108, v221
	v_add_f32_e32 v221, v109, v221
	v_add_f32_e32 v221, v110, v221
	v_add_f32_e32 v221, v111, v221
	v_fma_f32 v185, v185, v219, v221
	v_mul_f32_e32 v32, v219, v32
	v_mul_f32_e32 v33, v219, v33
	v_mul_f32_e32 v34, v219, v34
	v_mul_f32_e32 v35, v219, v35
	v_mul_f32_e32 v36, v219, v36
	v_mul_f32_e32 v37, v219, v37
	v_mul_f32_e32 v38, v219, v38
	v_mul_f32_e32 v39, v219, v39
	v_mul_f32_e32 v40, v219, v40
	v_mul_f32_e32 v41, v219, v41
	v_mul_f32_e32 v42, v219, v42
	v_mul_f32_e32 v43, v219, v43
	v_mul_f32_e32 v44, v219, v44
	v_mul_f32_e32 v45, v219, v45
	v_mul_f32_e32 v46, v219, v46
	v_mul_f32_e32 v47, v219, v47
	v_cvt_pk_bf16_f32 v152, v96, v97
	v_cvt_pk_bf16_f32 v153, v98, v99
	v_cvt_pk_bf16_f32 v154, v100, v101
	v_cvt_pk_bf16_f32 v155, v102, v103
	v_cvt_pk_bf16_f32 v156, v104, v105
	v_cvt_pk_bf16_f32 v157, v106, v107
	v_cvt_pk_bf16_f32 v158, v108, v109
	v_cvt_pk_bf16_f32 v159, v110, v111
	ds_read_b64 v[128:129], v231 offset:4096
	ds_read_b64 v[130:131], v233 offset:4096
	ds_read_b64 v[132:133], v232 offset:4096
	ds_read_b64 v[134:135], v234 offset:4096
	ds_read_b64 v[136:137], v231 offset:6144
	ds_read_b64 v[138:139], v233 offset:6144
	ds_read_b64 v[140:141], v232 offset:6144
	ds_read_b64 v[142:143], v234 offset:6144
	s_waitcnt lgkmcnt(8)
	v_mfma_f32_16x16x32_bf16 v[16:19], v[112:115], v[144:147], v[16:19]
	v_mfma_f32_16x16x32_bf16 v[32:35], v[112:115], v[152:155], v[32:35]
	v_mfma_f32_16x16x32_bf16 v[16:19], v[116:119], v[148:151], v[16:19]
	v_mfma_f32_16x16x32_bf16 v[32:35], v[116:119], v[156:159], v[32:35]
	v_mfma_f32_16x16x32_bf16 v[20:23], v[120:123], v[144:147], v[20:23]
	v_mfma_f32_16x16x32_bf16 v[36:39], v[120:123], v[152:155], v[36:39]
	v_mfma_f32_16x16x32_bf16 v[20:23], v[124:127], v[148:151], v[20:23]
	v_mfma_f32_16x16x32_bf16 v[36:39], v[124:127], v[156:159], v[36:39]
	s_waitcnt lgkmcnt(0)
	v_mfma_f32_16x16x32_bf16 v[24:27], v[128:131], v[144:147], v[24:27]
	v_mfma_f32_16x16x32_bf16 v[40:43], v[128:131], v[152:155], v[40:43]
	v_mfma_f32_16x16x32_bf16 v[24:27], v[132:135], v[148:151], v[24:27]
	v_mfma_f32_16x16x32_bf16 v[40:43], v[132:135], v[156:159], v[40:43]
	v_mfma_f32_16x16x32_bf16 v[28:31], v[136:139], v[144:147], v[28:31]
	v_mfma_f32_16x16x32_bf16 v[44:47], v[136:139], v[152:155], v[44:47]
	v_mfma_f32_16x16x32_bf16 v[28:31], v[140:143], v[148:151], v[28:31]
	v_mfma_f32_16x16x32_bf16 v[44:47], v[140:143], v[156:159], v[44:47]
	s_branch .Lp4_sel_next
; DEVI f32x4 mfma16(bf16x8 a, bf16x8 b, f32x4 c) { return __builtin_amdgcn_mfma_f32_16x16x32_bf16(a, b, c, 0, 0, 0); }
; template <int DH, int NQ, int LDK, class MaskF>
; DEVI void attn_qk(const u16* sK, const bf16x8 (&qf)[NQ][DH / 32], f32x4 (&o)[NQ][DH / 16], float (&m)[NQ], float (&l)[NQ],
;                   float c2, int lane, MaskF valid, bf16x8 (&pb)[NQ][2]) {
;   const int col = lane & 15, quad = lane >> 4;
;   f32x4 s[NQ][4];
;   __builtin_amdgcn_s_setprio(1);
; #pragma unroll
;   for (int kt = 0; kt < 4; ++kt) {
; #pragma unroll
;     for (int qt = 0; qt < NQ; ++qt) s[qt][kt] = f32x4{0.f, 0.f, 0.f, 0.f};
; #pragma unroll
;     for (int ks = 0; ks < DH / 32; ++ks) {
;       const bf16x8 kf = *(const bf16x8*)(sK + (16 * kt + col) * LDK + 32 * ks + 8 * quad);
; #pragma unroll
;       for (int qt = 0; qt < NQ; ++qt) s[qt][kt] = mfma16(kf, qf[qt][ks], s[qt][kt]);
;     }
;   }
;   __builtin_amdgcn_s_setprio(0);
; #pragma unroll
;   for (int qt = 0; qt < NQ; ++qt) {
;     float mx = -1e30f;
; #pragma unroll
;     for (int kt = 0; kt < 4; ++kt)
; #pragma unroll
;       for (int r = 0; r < 4; ++r) {
;         const bool v = valid(qt, 16 * kt + 4 * quad + r);
;         const float sv = v ? s[qt][kt][r] : -1e30f;
;         s[qt][kt][r] = sv;
;         mx = fmaxf(mx, sv);
;       }
; DEVI void phase_nsa(const Params& p, unsigned char* smem) {
;     ...
;         const int lim0 = ((sm[0] >> kb) & 1u) ? tq[0] : -1, lim1 = ((sm[1] >> kb) & 1u) ? tq[1] : -1;
;         attn_tile<64, 2, 72, 72>(sK, sVt, qf, o, m, l, c2, lane, [&](int qt, int kl) {
;           return (kb * 64 + kl) <= (qt ? lim1 : lim0);
.Lp4_sel_masked:
	v_add_u32_e32 v227, s46, v235
	v_add_u32_e32 v228, s46, v236
	v_add_u32_e32 v231, s46, v237
	v_add_u32_e32 v233, s46, v239
	v_add_u32_e32 v232, s46, v238
	v_add_u32_e32 v234, s46, v240
	ds_read_b128 v[112:115], v227
	ds_read_b128 v[116:119], v228
	ds_read_b128 v[120:123], v227 offset:2048
	ds_read_b128 v[124:127], v228 offset:2048
	ds_read_b128 v[128:131], v227 offset:4096
	ds_read_b128 v[132:135], v228 offset:4096
	ds_read_b128 v[136:139], v227 offset:6144
	ds_read_b128 v[140:143], v228 offset:6144
	s_waitcnt lgkmcnt(7)
	v_mfma_f32_16x16x32_bf16 v[80:83], v[112:115], v[0:3], 0
	v_mfma_f32_16x16x32_bf16 v[96:99], v[112:115], v[8:11], 0
	s_waitcnt lgkmcnt(6)
	v_mfma_f32_16x16x32_bf16 v[80:83], v[116:119], v[4:7], v[80:83]
	v_mfma_f32_16x16x32_bf16 v[96:99], v[116:119], v[12:15], v[96:99]
	s_waitcnt lgkmcnt(5)
	v_mfma_f32_16x16x32_bf16 v[84:87], v[120:123], v[0:3], 0
	v_mfma_f32_16x16x32_bf16 v[100:103], v[120:123], v[8:11], 0
	s_waitcnt lgkmcnt(4)
	v_mfma_f32_16x16x32_bf16 v[84:87], v[124:127], v[4:7], v[84:87]
	v_mfma_f32_16x16x32_bf16 v[100:103], v[124:127], v[12:15], v[100:103]
	s_waitcnt lgkmcnt(3)
	v_mfma_f32_16x16x32_bf16 v[88:91], v[128:131], v[0:3], 0
	v_mfma_f32_16x16x32_bf16 v[104:107], v[128:131], v[8:11], 0
	s_waitcnt lgkmcnt(2)
	v_mfma_f32_16x16x32_bf16 v[88:91], v[132:135], v[4:7], v[88:91]
	v_mfma_f32_16x16x32_bf16 v[104:107], v[132:135], v[12:15], v[104:107]
	s_waitcnt lgkmcnt(1)
	v_mfma_f32_16x16x32_bf16 v[92:95], v[136:139], v[0:3], 0
	v_mfma_f32_16x16x32_bf16 v[108:111], v[136:139], v[8:11], 0
	s_waitcnt lgkmcnt(0)
	v_mfma_f32_16x16x32_bf16 v[92:95], v[140:143], v[4:7], v[92:95]
	v_mfma_f32_16x16x32_bf16 v[108:111], v[140:143], v[12:15], v[108:111]
	ds_read_b64 v[112:113], v231 offset:0
	ds_read_b64 v[114:115], v233 offset:0
	ds_read_b64 v[116:117], v232 offset:0
	ds_read_b64 v[118:119], v234 offset:0
	ds_read_b64 v[120:121], v231 offset:2048
	ds_read_b64 v[122:123], v233 offset:2048
	ds_read_b64 v[124:125], v232 offset:2048
	ds_read_b64 v[126:127], v234 offset:2048
	s_nop 3
	v_subrev_u32_e32 v222, s30, v207
	v_subrev_u32_e32 v223, 0, v222
	v_cmp_ge_u32_e64 s[32:33], s41, v223
	v_subrev_u32_e32 v224, 1, v222
	v_cmp_ge_u32_e64 s[34:35], s41, v224
	v_subrev_u32_e32 v225, 2, v222
	v_cmp_ge_u32_e64 s[36:37], s41, v225
	v_subrev_u32_e32 v226, 3, v222
	v_cmp_ge_u32_e64 s[38:39], s41, v226
	v_cndmask_b32_e64 v80, v230, v80, s[32:33]
	v_cndmask_b32_e64 v81, v230, v81, s[34:35]
	v_cndmask_b32_e64 v82, v230, v82, s[36:37]
	v_cndmask_b32_e64 v83, v230, v83, s[38:39]
	v_subrev_u32_e32 v223, 16, v222
	v_cmp_ge_u32_e64 s[32:33], s41, v223
	v_subrev_u32_e32 v224, 17, v222
	v_cmp_ge_u32_e64 s[34:35], s41, v224
	v_subrev_u32_e32 v225, 18, v222
	v_cmp_ge_u32_e64 s[36:37], s41, v225
	v_subrev_u32_e32 v226, 19, v222
	v_cmp_ge_u32_e64 s[38:39], s41, v226
	v_cndmask_b32_e64 v84, v230, v84, s[32:33]
	v_cndmask_b32_e64 v85, v230, v85, s[34:35]
	v_cndmask_b32_e64 v86, v230, v86, s[36:37]
	v_cndmask_b32_e64 v87, v230, v87, s[38:39]
	v_subrev_u32_e32 v223, 32, v222
	v_cmp_ge_u32_e64 s[32:33], s41, v223
	v_subrev_u32_e32 v224, 33, v222
	v_cmp_ge_u32_e64 s[34:35], s41, v224
	v_subrev_u32_e32 v225, 34, v222
	v_cmp_ge_u32_e64 s[36:37], s41, v225
	v_subrev_u32_e32 v226, 35, v222
	v_cmp_ge_u32_e64 s[38:39], s41, v226
	v_cndmask_b32_e64 v88, v230, v88, s[32:33]
	v_cndmask_b32_e64 v89, v230, v89, s[34:35]
	v_cndmask_b32_e64 v90, v230, v90, s[36:37]
	v_cndmask_b32_e64 v91, v230, v91, s[38:39]
	v_subrev_u32_e32 v223, 48, v222
	v_cmp_ge_u32_e64 s[32:33], s41, v223
	v_subrev_u32_e32 v224, 49, v222
	v_cmp_ge_u32_e64 s[34:35], s41, v224
	v_subrev_u32_e32 v225, 50, v222
	v_cmp_ge_u32_e64 s[36:37], s41, v225
	v_subrev_u32_e32 v226, 51, v222
	v_cmp_ge_u32_e64 s[38:39], s41, v226
	v_cndmask_b32_e64 v92, v230, v92, s[32:33]
	v_cndmask_b32_e64 v93, v230, v93, s[34:35]
	v_cndmask_b32_e64 v94, v230, v94, s[36:37]
	v_cndmask_b32_e64 v95, v230, v95, s[38:39]
	v_max3_f32 v215, v80, v81, v82
	v_max3_f32 v215, v215, v83, v84
	v_max3_f32 v215, v215, v85, v86
	v_max3_f32 v215, v215, v87, v88
	v_max3_f32 v215, v215, v89, v90
	v_max3_f32 v215, v215, v91, v92
	v_max3_f32 v215, v215, v93, v94
	v_max_f32_e32 v215, v95, v215
	ds_bpermute_b32 v216, v195, v215
	s_waitcnt lgkmcnt(0)
; DEVI unsigned pack2(float a, float b) { return (unsigned)f2bf(a) | ((unsigned)f2bf(b) << 16); }
; DEVI float fexp2(float x) { return __builtin_amdgcn_exp2f(x); }
; template <int DH, int NQ, int LDK, class MaskF>
; DEVI void attn_qk(const u16* sK, const bf16x8 (&qf)[NQ][DH / 32], f32x4 (&o)[NQ][DH / 16], float (&m)[NQ], float (&l)[NQ],
;                   float c2, int lane, MaskF valid, bf16x8 (&pb)[NQ][2]) {
;     ...
;   for (int qt = 0; qt < NQ; ++qt) {
;     float mx = -1e30f;
; #pragma unroll
;     for (int kt = 0; kt < 4; ++kt)
; #pragma unroll
;       for (int r = 0; r < 4; ++r) {
;         const bool v = valid(qt, 16 * kt + 4 * quad + r);
;         const float sv = v ? s[qt][kt][r] : -1e30f;
;         s[qt][kt][r] = sv;
;         mx = fmaxf(mx, sv);
;       }
;     mx = fmaxf(mx, __shfl_xor(mx, 16));
;     mx = fmaxf(mx, __shfl_xor(mx, 32));
;     const float mn = fmaxf(m[qt], mx);
;     const float alpha = fexp2((m[qt] - mn) * c2);
;     m[qt] = mn;
;     const float mc = fmaxf(mn, -1e20f) * c2;
;     float ps = 0.f;
; #pragma unroll
;     for (int kt = 0; kt < 4; ++kt)
; #pragma unroll
;       for (int r = 0; r < 4; ++r) {
;         const float pv = fexp2(__builtin_fmaf(s[qt][kt][r], c2, -mc));
;         ps += pv;
;         s[qt][kt][r] = pv;
;       }
;     l[qt] = l[qt] * alpha + ps;
; #pragma unroll
;     for (int dt = 0; dt < DH / 16; ++dt) o[qt][dt] *= alpha;
; #pragma unroll
;     for (int kk = 0; kk < 2; ++kk) {
;       union { bf16x8 v; unsigned u[4]; } cv;
;       cv.u[0] = pack2(s[qt][2 * kk][0], s[qt][2 * kk][1]);
;       cv.u[1] = pack2(s[qt][2 * kk][2], s[qt][2 * kk][3]);
;       cv.u[2] = pack2(s[qt][2 * kk + 1][0], s[qt][2 * kk + 1][1]);
;       cv.u[3] = pack2(s[qt][2 * kk + 1][2], s[qt][2 * kk + 1][3]);
;       pb[qt][kk] = cv.v;
;     }
;   }
	v_max_f32_e32 v215, v216, v215
	v_mov_b32_e32 v216, v215
	v_mov_b32_e32 v217, v215
	s_nop 1
	v_permlane32_swap_b32_e32 v216, v217
	v_max_f32_e32 v215, v216, v217
	v_max_f32_e32 v218, v182, v215
	v_sub_f32_e32 v219, v182, v218
	v_mul_f32_e32 v219, v200, v219
	v_exp_f32_e32 v219, v219
	v_mov_b32_e32 v182, v218
	v_max_f32_e32 v220, 0xe0ad78ec, v218
	v_mul_f32_e32 v220, 0xbe38aa3b, v220
	v_fma_f32 v80, v80, v200, v220
	v_exp_f32_e32 v80, v80
	v_fma_f32 v81, v81, v200, v220
	v_exp_f32_e32 v81, v81
	v_fma_f32 v82, v82, v200, v220
	v_exp_f32_e32 v82, v82
	v_fma_f32 v83, v83, v200, v220
	v_exp_f32_e32 v83, v83
	v_fma_f32 v84, v84, v200, v220
	v_exp_f32_e32 v84, v84
	v_fma_f32 v85, v85, v200, v220
	v_exp_f32_e32 v85, v85
	v_fma_f32 v86, v86, v200, v220
	v_exp_f32_e32 v86, v86
	v_fma_f32 v87, v87, v200, v220
	v_exp_f32_e32 v87, v87
	v_fma_f32 v88, v88, v200, v220
	v_exp_f32_e32 v88, v88
	v_fma_f32 v89, v89, v200, v220
	v_exp_f32_e32 v89, v89
	v_fma_f32 v90, v90, v200, v220
	v_exp_f32_e32 v90, v90
	v_fma_f32 v91, v91, v200, v220
	v_exp_f32_e32 v91, v91
	v_fma_f32 v92, v92, v200, v220
	v_exp_f32_e32 v92, v92
	v_fma_f32 v93, v93, v200, v220
	v_exp_f32_e32 v93, v93
	v_fma_f32 v94, v94, v200, v220
	v_exp_f32_e32 v94, v94
	v_fma_f32 v95, v95, v200, v220
	v_exp_f32_e32 v95, v95
	s_nop 0
	v_add_f32_e32 v221, v80, v81
	v_add_f32_e32 v221, v82, v221
	v_add_f32_e32 v221, v83, v221
	v_add_f32_e32 v221, v84, v221
	v_add_f32_e32 v221, v85, v221
	v_add_f32_e32 v221, v86, v221
	v_add_f32_e32 v221, v87, v221
	v_add_f32_e32 v221, v88, v221
	v_add_f32_e32 v221, v89, v221
	v_add_f32_e32 v221, v90, v221
	v_add_f32_e32 v221, v91, v221
	v_add_f32_e32 v221, v92, v221
	v_add_f32_e32 v221, v93, v221
	v_add_f32_e32 v221, v94, v221
	v_add_f32_e32 v221, v95, v221
	v_fma_f32 v184, v184, v219, v221
	v_mul_f32_e32 v16, v219, v16
	v_mul_f32_e32 v17, v219, v17
	v_mul_f32_e32 v18, v219, v18
	v_mul_f32_e32 v19, v219, v19
	v_mul_f32_e32 v20, v219, v20
	v_mul_f32_e32 v21, v219, v21
	v_mul_f32_e32 v22, v219, v22
	v_mul_f32_e32 v23, v219, v23
	v_mul_f32_e32 v24, v219, v24
	v_mul_f32_e32 v25, v219, v25
	v_mul_f32_e32 v26, v219, v26
	v_mul_f32_e32 v27, v219, v27
	v_mul_f32_e32 v28, v219, v28
	v_mul_f32_e32 v29, v219, v29
	v_mul_f32_e32 v30, v219, v30
	v_mul_f32_e32 v31, v219, v31
	v_cvt_pk_bf16_f32 v144, v80, v81
	v_cvt_pk_bf16_f32 v145, v82, v83
	v_cvt_pk_bf16_f32 v146, v84, v85
	v_cvt_pk_bf16_f32 v147, v86, v87
	v_cvt_pk_bf16_f32 v148, v88, v89
	v_cvt_pk_bf16_f32 v149, v90, v91
	v_cvt_pk_bf16_f32 v150, v92, v93
	v_cvt_pk_bf16_f32 v151, v94, v95
	v_subrev_u32_e32 v222, s30, v208
	v_subrev_u32_e32 v223, 0, v222
	v_cmp_ge_u32_e64 s[32:33], s41, v223
	v_subrev_u32_e32 v224, 1, v222
	v_cmp_ge_u32_e64 s[34:35], s41, v224
	v_subrev_u32_e32 v225, 2, v222
	v_cmp_ge_u32_e64 s[36:37], s41, v225
	v_subrev_u32_e32 v226, 3, v222
	v_cmp_ge_u32_e64 s[38:39], s41, v226
	v_cndmask_b32_e64 v96, v230, v96, s[32:33]
	v_cndmask_b32_e64 v97, v230, v97, s[34:35]
	v_cndmask_b32_e64 v98, v230, v98, s[36:37]
	v_cndmask_b32_e64 v99, v230, v99, s[38:39]
	v_subrev_u32_e32 v223, 16, v222
	v_cmp_ge_u32_e64 s[32:33], s41, v223
	v_subrev_u32_e32 v224, 17, v222
	v_cmp_ge_u32_e64 s[34:35], s41, v224
	v_subrev_u32_e32 v225, 18, v222
	v_cmp_ge_u32_e64 s[36:37], s41, v225
	v_subrev_u32_e32 v226, 19, v222
	v_cmp_ge_u32_e64 s[38:39], s41, v226
	v_cndmask_b32_e64 v100, v230, v100, s[32:33]
	v_cndmask_b32_e64 v101, v230, v101, s[34:35]
	v_cndmask_b32_e64 v102, v230, v102, s[36:37]
	v_cndmask_b32_e64 v103, v230, v103, s[38:39]
	v_subrev_u32_e32 v223, 32, v222
	v_cmp_ge_u32_e64 s[32:33], s41, v223
	v_subrev_u32_e32 v224, 33, v222
	v_cmp_ge_u32_e64 s[34:35], s41, v224
	v_subrev_u32_e32 v225, 34, v222
	v_cmp_ge_u32_e64 s[36:37], s41, v225
	v_subrev_u32_e32 v226, 35, v222
	v_cmp_ge_u32_e64 s[38:39], s41, v226
	v_cndmask_b32_e64 v104, v230, v104, s[32:33]
	v_cndmask_b32_e64 v105, v230, v105, s[34:35]
	v_cndmask_b32_e64 v106, v230, v106, s[36:37]
	v_cndmask_b32_e64 v107, v230, v107, s[38:39]
	v_subrev_u32_e32 v223, 48, v222
	v_cmp_ge_u32_e64 s[32:33], s41, v223
	v_subrev_u32_e32 v224, 49, v222
	v_cmp_ge_u32_e64 s[34:35], s41, v224
	v_subrev_u32_e32 v225, 50, v222
	v_cmp_ge_u32_e64 s[36:37], s41, v225
	v_subrev_u32_e32 v226, 51, v222
	v_cmp_ge_u32_e64 s[38:39], s41, v226
	v_cndmask_b32_e64 v108, v230, v108, s[32:33]
	v_cndmask_b32_e64 v109, v230, v109, s[34:35]
	v_cndmask_b32_e64 v110, v230, v110, s[36:37]
	v_cndmask_b32_e64 v111, v230, v111, s[38:39]
	v_max3_f32 v215, v96, v97, v98
	v_max3_f32 v215, v215, v99, v100
	v_max3_f32 v215, v215, v101, v102
	v_max3_f32 v215, v215, v103, v104
	v_max3_f32 v215, v215, v105, v106
	v_max3_f32 v215, v215, v107, v108
	v_max3_f32 v215, v215, v109, v110
	v_max_f32_e32 v215, v111, v215
	ds_bpermute_b32 v216, v195, v215
	s_waitcnt lgkmcnt(0)
; template <int DH, int NQ, int LDK, class MaskF>
; DEVI void attn_qk(const u16* sK, const bf16x8 (&qf)[NQ][DH / 32], f32x4 (&o)[NQ][DH / 16], float (&m)[NQ], float (&l)[NQ],
;                   float c2, int lane, MaskF valid, bf16x8 (&pb)[NQ][2]) {
;     ...
;     mx = fmaxf(mx, __shfl_xor(mx, 16));
;     mx = fmaxf(mx, __shfl_xor(mx, 32));
;     const float mn = fmaxf(m[qt], mx);
;     const float alpha = fexp2((m[qt] - mn) * c2);
;     m[qt] = mn;
;     const float mc = fmaxf(mn, -1e20f) * c2;
;     float ps = 0.f;
; #pragma unroll
;     for (int kt = 0; kt < 4; ++kt)
; #pragma unroll
;       for (int r = 0; r < 4; ++r) {
;         const float pv = fexp2(__builtin_fmaf(s[qt][kt][r], c2, -mc));
;         ps += pv;
;         s[qt][kt][r] = pv;
;       }
;     l[qt] = l[qt] * alpha + ps;
; #pragma unroll
;     for (int dt = 0; dt < DH / 16; ++dt) o[qt][dt] *= alpha;
; #pragma unroll
;     for (int kk = 0; kk < 2; ++kk) {
;       union { bf16x8 v; unsigned u[4]; } cv;
;       cv.u[0] = pack2(s[qt][2 * kk][0], s[qt][2 * kk][1]);
;       cv.u[1] = pack2(s[qt][2 * kk][2], s[qt][2 * kk][3]);
;       cv.u[2] = pack2(s[qt][2 * kk + 1][0], s[qt][2 * kk + 1][1]);
;       cv.u[3] = pack2(s[qt][2 * kk + 1][2], s[qt][2 * kk + 1][3]);
;       pb[qt][kk] = cv.v;
;     }
;   }
; }
; template <int DH, int NQ, int LDV>
; DEVI void attn_pv(const u16* sVt, const bf16x8 (&pb)[NQ][2], f32x4 (&o)[NQ][DH / 16], int lane) {
;   const int col = lane & 15, quad = lane >> 4;
;   __builtin_amdgcn_s_setprio(1);
; #pragma unroll
;   for (int dt = 0; dt < DH / 16; ++dt) {
; #pragma unroll
;     for (int kk = 0; kk < 2; ++kk) {
;       union { bf16x8 v; uint2 h[2]; } cv;
;       cv.h[0] = *(const uint2*)(sVt + (16 * dt + col) * LDV + 32 * kk + 4 * quad);
;       cv.h[1] = *(const uint2*)(sVt + (16 * dt + col) * LDV + 32 * kk + 16 + 4 * quad);
; #pragma unroll
;       for (int qt = 0; qt < NQ; ++qt) o[qt][dt] = mfma16(cv.v, pb[qt][kk], o[qt][dt]);
;     }
;   }
;   __builtin_amdgcn_s_setprio(0);
; DEVI void phase_nsa(const Params& p, unsigned char* smem) {
;     ...
;       while (kb >= 0) {
;         rem &= rem - 1u;
;         const int nkb = rem ? (__ffs((int)rem) - 1) : -1;
;         __syncthreads();
;         STOREKV_()
;         if (nkb >= 0) { LOADKV_(nkb, C_KS, p.vts) }
;         __syncthreads();
;         const int lim0 = ((sm[0] >> kb) & 1u) ? tq[0] : -1, lim1 = ((sm[1] >> kb) & 1u) ? tq[1] : -1;
	v_max_f32_e32 v215, v216, v215
	v_mov_b32_e32 v216, v215
	v_mov_b32_e32 v217, v215
	s_nop 1
	v_permlane32_swap_b32_e32 v216, v217
	v_max_f32_e32 v215, v216, v217
	v_max_f32_e32 v218, v183, v215
	v_sub_f32_e32 v219, v183, v218
	v_mul_f32_e32 v219, v200, v219
	v_exp_f32_e32 v219, v219
	v_mov_b32_e32 v183, v218
	v_max_f32_e32 v220, 0xe0ad78ec, v218
	v_mul_f32_e32 v220, 0xbe38aa3b, v220
	v_fma_f32 v96, v96, v200, v220
	v_exp_f32_e32 v96, v96
	v_fma_f32 v97, v97, v200, v220
	v_exp_f32_e32 v97, v97
	v_fma_f32 v98, v98, v200, v220
	v_exp_f32_e32 v98, v98
	v_fma_f32 v99, v99, v200, v220
	v_exp_f32_e32 v99, v99
	v_fma_f32 v100, v100, v200, v220
	v_exp_f32_e32 v100, v100
	v_fma_f32 v101, v101, v200, v220
	v_exp_f32_e32 v101, v101
	v_fma_f32 v102, v102, v200, v220
	v_exp_f32_e32 v102, v102
	v_fma_f32 v103, v103, v200, v220
	v_exp_f32_e32 v103, v103
	v_fma_f32 v104, v104, v200, v220
	v_exp_f32_e32 v104, v104
	v_fma_f32 v105, v105, v200, v220
	v_exp_f32_e32 v105, v105
	v_fma_f32 v106, v106, v200, v220
	v_exp_f32_e32 v106, v106
	v_fma_f32 v107, v107, v200, v220
	v_exp_f32_e32 v107, v107
	v_fma_f32 v108, v108, v200, v220
	v_exp_f32_e32 v108, v108
	v_fma_f32 v109, v109, v200, v220
	v_exp_f32_e32 v109, v109
	v_fma_f32 v110, v110, v200, v220
	v_exp_f32_e32 v110, v110
	v_fma_f32 v111, v111, v200, v220
	v_exp_f32_e32 v111, v111
	s_nop 0
	v_add_f32_e32 v221, v96, v97
	v_add_f32_e32 v221, v98, v221
	v_add_f32_e32 v221, v99, v221
	v_add_f32_e32 v221, v100, v221
	v_add_f32_e32 v221, v101, v221
	v_add_f32_e32 v221, v102, v221
	v_add_f32_e32 v221, v103, v221
	v_add_f32_e32 v221, v104, v221
	v_add_f32_e32 v221, v105, v221
	v_add_f32_e32 v221, v106, v221
	v_add_f32_e32 v221, v107, v221
	v_add_f32_e32 v221, v108, v221
	v_add_f32_e32 v221, v109, v221
	v_add_f32_e32 v221, v110, v221
	v_add_f32_e32 v221, v111, v221
	v_fma_f32 v185, v185, v219, v221
	v_mul_f32_e32 v32, v219, v32
	v_mul_f32_e32 v33, v219, v33
	v_mul_f32_e32 v34, v219, v34
	v_mul_f32_e32 v35, v219, v35
	v_mul_f32_e32 v36, v219, v36
	v_mul_f32_e32 v37, v219, v37
	v_mul_f32_e32 v38, v219, v38
	v_mul_f32_e32 v39, v219, v39
	v_mul_f32_e32 v40, v219, v40
	v_mul_f32_e32 v41, v219, v41
	v_mul_f32_e32 v42, v219, v42
	v_mul_f32_e32 v43, v219, v43
	v_mul_f32_e32 v44, v219, v44
	v_mul_f32_e32 v45, v219, v45
	v_mul_f32_e32 v46, v219, v46
	v_mul_f32_e32 v47, v219, v47
	v_cvt_pk_bf16_f32 v152, v96, v97
	v_cvt_pk_bf16_f32 v153, v98, v99
	v_cvt_pk_bf16_f32 v154, v100, v101
	v_cvt_pk_bf16_f32 v155, v102, v103
	v_cvt_pk_bf16_f32 v156, v104, v105
	v_cvt_pk_bf16_f32 v157, v106, v107
	v_cvt_pk_bf16_f32 v158, v108, v109
	v_cvt_pk_bf16_f32 v159, v110, v111
	ds_read_b64 v[128:129], v231 offset:4096
	ds_read_b64 v[130:131], v233 offset:4096
	ds_read_b64 v[132:133], v232 offset:4096
	ds_read_b64 v[134:135], v234 offset:4096
	ds_read_b64 v[136:137], v231 offset:6144
	ds_read_b64 v[138:139], v233 offset:6144
	ds_read_b64 v[140:141], v232 offset:6144
	ds_read_b64 v[142:143], v234 offset:6144
	s_waitcnt lgkmcnt(8)
	v_mfma_f32_16x16x32_bf16 v[16:19], v[112:115], v[144:147], v[16:19]
	v_mfma_f32_16x16x32_bf16 v[32:35], v[112:115], v[152:155], v[32:35]
	v_mfma_f32_16x16x32_bf16 v[16:19], v[116:119], v[148:151], v[16:19]
	v_mfma_f32_16x16x32_bf16 v[32:35], v[116:119], v[156:159], v[32:35]
	v_mfma_f32_16x16x32_bf16 v[20:23], v[120:123], v[144:147], v[20:23]
	v_mfma_f32_16x16x32_bf16 v[36:39], v[120:123], v[152:155], v[36:39]
	v_mfma_f32_16x16x32_bf16 v[20:23], v[124:127], v[148:151], v[20:23]
	v_mfma_f32_16x16x32_bf16 v[36:39], v[124:127], v[156:159], v[36:39]
	s_waitcnt lgkmcnt(0)
	v_mfma_f32_16x16x32_bf16 v[24:27], v[128:131], v[144:147], v[24:27]
	v_mfma_f32_16x16x32_bf16 v[40:43], v[128:131], v[152:155], v[40:43]
	v_mfma_f32_16x16x32_bf16 v[24:27], v[132:135], v[148:151], v[24:27]
	v_mfma_f32_16x16x32_bf16 v[40:43], v[132:135], v[156:159], v[40:43]
	v_mfma_f32_16x16x32_bf16 v[28:31], v[136:139], v[144:147], v[28:31]
	v_mfma_f32_16x16x32_bf16 v[44:47], v[136:139], v[152:155], v[44:47]
	v_mfma_f32_16x16x32_bf16 v[28:31], v[140:143], v[148:151], v[28:31]
	v_mfma_f32_16x16x32_bf16 v[44:47], v[140:143], v[156:159], v[44:47]
.Lp4_sel_next:
	s_mov_b32 s26, s47
	s_mov_b32 s47, s48
	s_mov_b32 s48, s49
	s_add_u32 s46, s46, 0x4000
	s_and_b32 s46, s46, 0xffff
	s_ff1_i32_b32 s49, s25
	s_add_u32 s22, s25, -1
	s_and_b32 s25, s25, s22
	s_cmp_lt_i32 s26, 0
	s_cbranch_scc0 .Lp4_sel_loop
; DEVI void phase_nsa(const Params& p, unsigned char* smem) {
;     ...
; #pragma unroll
;       for (int qt = 0; qt < 2; ++qt) {
;         float lt = l[qt];
;         lt += __shfl_xor(lt, 16);
;         lt += __shfl_xor(lt, 32);
;         const float sc = lt > 0.f ? gate[qt][1] / lt : 0.f;
; #pragma unroll
;         for (int dt = 0; dt < 4; ++dt) comb[qt][dt] += o[qt][dt] * sc;
;       }
;     }
;     {
;       float m[2] = {-1e30f, -1e30f}, l[2] = {0.f, 0.f};
;       f32x4 o[2][4];
; #pragma unroll
;       for (int qt = 0; qt < 2; ++qt)
; #pragma unroll
;         for (int dt = 0; dt < 4; ++dt) o[qt][dt] = f32x4{0.f, 0.f, 0.f, 0.f};
;       const int kblo = (q0 >= 511) ? ((q0 - 511) >> 6) : 0;
;       uint4 rk0, rk1, rv0, rv1;
;       const int lr0 = tid >> 3, lch = (tid & 7) << 3;
;       int kb = kblo;
;       LOADKV_(kb, C_KW, p.vtw)
; #pragma unroll 1
;       while (kb >= 0) {
;         const int nkb = (kb < kbmax) ? kb + 1 : -1;
;         __syncthreads();
;         STOREKV_()
;         if (nkb >= 0) { LOADKV_(nkb, C_KW, p.vtw) }
.Lp4_sel_end:
	s_nop 7
	v_mov_b32_e32 v215, v184
	ds_bpermute_b32 v216, v195, v215
	s_waitcnt lgkmcnt(0)
	v_add_f32_e32 v215, v216, v215
	v_mov_b32_e32 v216, v215
	v_mov_b32_e32 v217, v215
	s_nop 1
	v_permlane32_swap_b32_e32 v216, v217
	v_add_f32_e32 v215, v216, v217
	v_rcp_f32_e32 v218, v215
	s_nop 0
	v_fma_f32 v219, -v215, v218, 1.0
	v_fma_f32 v218, v219, v218, v218
	v_mul_f32_e32 v218, v177, v218
	v_cmp_lt_f32_e64 s[32:33], 0, v215
	v_mov_b32_e32 v220, 0
	s_nop 0
	v_cndmask_b32_e64 v218, v220, v218, s[32:33]
	v_fma_f32 v48, v16, v218, v48
	v_fma_f32 v49, v17, v218, v49
	v_fma_f32 v50, v18, v218, v50
	v_fma_f32 v51, v19, v218, v51
	v_fma_f32 v52, v20, v218, v52
	v_fma_f32 v53, v21, v218, v53
	v_fma_f32 v54, v22, v218, v54
	v_fma_f32 v55, v23, v218, v55
	v_fma_f32 v56, v24, v218, v56
	v_fma_f32 v57, v25, v218, v57
	v_fma_f32 v58, v26, v218, v58
	v_fma_f32 v59, v27, v218, v59
	v_fma_f32 v60, v28, v218, v60
	v_fma_f32 v61, v29, v218, v61
	v_fma_f32 v62, v30, v218, v62
	v_fma_f32 v63, v31, v218, v63
	v_mov_b32_e32 v215, v185
	ds_bpermute_b32 v216, v195, v215
	s_waitcnt lgkmcnt(0)
	v_add_f32_e32 v215, v216, v215
	v_mov_b32_e32 v216, v215
	v_mov_b32_e32 v217, v215
	s_nop 1
	v_permlane32_swap_b32_e32 v216, v217
	v_add_f32_e32 v215, v216, v217
	v_rcp_f32_e32 v218, v215
	s_nop 0
	v_fma_f32 v219, -v215, v218, 1.0
	v_fma_f32 v218, v219, v218, v218
	v_mul_f32_e32 v218, v180, v218
	v_cmp_lt_f32_e64 s[32:33], 0, v215
	v_mov_b32_e32 v220, 0
	s_nop 0
	v_cndmask_b32_e64 v218, v220, v218, s[32:33]
	v_fma_f32 v64, v32, v218, v64
	v_fma_f32 v65, v33, v218, v65
	v_fma_f32 v66, v34, v218, v66
	v_fma_f32 v67, v35, v218, v67
	v_fma_f32 v68, v36, v218, v68
	v_fma_f32 v69, v37, v218, v69
	v_fma_f32 v70, v38, v218, v70
	v_fma_f32 v71, v39, v218, v71
	v_fma_f32 v72, v40, v218, v72
	v_fma_f32 v73, v41, v218, v73
	v_fma_f32 v74, v42, v218, v74
	v_fma_f32 v75, v43, v218, v75
	v_fma_f32 v76, v44, v218, v76
	v_fma_f32 v77, v45, v218, v77
	v_fma_f32 v78, v46, v218, v78
	v_fma_f32 v79, v47, v218, v79
	s_barrier
	s_mov_b32 s42, s6
	s_mov_b32 s43, s7
	s_lshl_b32 s31, s17, 7
	s_add_u32 s31, s31, 4096
	s_mov_b32 s41, 0x1ff
	v_mov_b32_e32 v16, 0
	v_mov_b32_e32 v17, 0
	v_mov_b32_e32 v18, 0
	v_mov_b32_e32 v19, 0
	v_mov_b32_e32 v20, 0
	v_mov_b32_e32 v21, 0
	v_mov_b32_e32 v22, 0
	v_mov_b32_e32 v23, 0
	v_mov_b32_e32 v24, 0
	v_mov_b32_e32 v25, 0
	v_mov_b32_e32 v26, 0
	v_mov_b32_e32 v27, 0
	v_mov_b32_e32 v28, 0
	v_mov_b32_e32 v29, 0
	v_mov_b32_e32 v30, 0
	v_mov_b32_e32 v31, 0
	v_mov_b32_e32 v32, 0
	v_mov_b32_e32 v33, 0
	v_mov_b32_e32 v34, 0
	v_mov_b32_e32 v35, 0
	v_mov_b32_e32 v36, 0
	v_mov_b32_e32 v37, 0
	v_mov_b32_e32 v38, 0
	v_mov_b32_e32 v39, 0
	v_mov_b32_e32 v40, 0
	v_mov_b32_e32 v41, 0
	v_mov_b32_e32 v42, 0
	v_mov_b32_e32 v43, 0
	v_mov_b32_e32 v44, 0
	v_mov_b32_e32 v45, 0
	v_mov_b32_e32 v46, 0
	v_mov_b32_e32 v47, 0
	v_mov_b32_e32 v182, 0xf149f2ca
	v_mov_b32_e32 v184, 0
	v_mov_b32_e32 v183, 0xf149f2ca
	v_mov_b32_e32 v185, 0
	s_mov_b32 s52, s45
	s_mov_b32 s26, s52
	s_add_u32 s22, s52, 1
	s_cmp_lt_i32 s52, s20
	s_cselect_b32 s22, s22, -1
	s_cmp_lt_i32 s52, 0
	s_cselect_b32 s52, -1, s22
	s_mov_b32 s47, s52
	s_add_u32 s22, s52, 1
	s_cmp_lt_i32 s52, s20
	s_cselect_b32 s22, s22, -1
	s_cmp_lt_i32 s52, 0
	s_cselect_b32 s52, -1, s22
	s_mov_b32 s48, s52
	s_add_u32 s22, s52, 1
	s_cmp_lt_i32 s52, s20
	s_cselect_b32 s22, s22, -1
	s_cmp_lt_i32 s52, 0
	s_cselect_b32 s52, -1, s22
	s_mov_b32 s49, s52
	s_add_u32 s22, s52, 1
	s_cmp_lt_i32 s52, s20
	s_cselect_b32 s22, s22, -1
	s_cmp_lt_i32 s52, 0
	s_cselect_b32 s52, -1, s22
	s_cmp_lt_i32 s26, 0
	s_cbranch_scc1 .Lp4_win_end
	s_mov_b32 s46, 0
	s_lshl_b32 s22, s16, 11
	s_lshl_b32 s23, s26, 6
	s_add_u32 s22, s22, s23
	s_mul_i32 s22, s22, 0x1240
	s_add_u32 s22, s22, s31
	s_mul_i32 s23, s18, 0x42000
	s_lshl_b32 s24, s26, 7
	s_add_u32 s23, s23, s24
	s_add_u32 s51, s46, s50
	s_mov_b32 m0, s51
	v_add_u32_e32 v211, s22, v201
	v_mov_b32_e32 v245, s1
	v_add_co_u32_e32 v244, vcc, s0, v211
	s_nop 1
	v_addc_co_u32_e32 v245, vcc, 0, v245, vcc
	global_load_lds_dwordx4 v[244:245], off
	s_add_u32 s51, s51, 1024
	s_mov_b32 m0, s51
	v_add_u32_e32 v212, s22, v202
	v_mov_b32_e32 v245, s1
	v_add_co_u32_e32 v244, vcc, s0, v212
	s_nop 1
	v_addc_co_u32_e32 v245, vcc, 0, v245, vcc
	global_load_lds_dwordx4 v[244:245], off
	s_add_u32 s51, s51, 7168
	s_mov_b32 m0, s51
	v_add_u32_e32 v213, s23, v203
	v_mov_b32_e32 v245, s43
	v_add_co_u32_e32 v244, vcc, s42, v213
	s_nop 1
	v_addc_co_u32_e32 v245, vcc, 0, v245, vcc
	global_load_lds_dwordx4 v[244:245], off
	s_add_u32 s51, s51, 1024
	s_mov_b32 m0, s51
	v_add_u32_e32 v214, s23, v204
	v_mov_b32_e32 v245, s43
	v_add_co_u32_e32 v244, vcc, s42, v214
	s_nop 1
	v_addc_co_u32_e32 v245, vcc, 0, v245, vcc
	global_load_lds_dwordx4 v[244:245], off
	s_movk_i32 s53, 0x4000
	s_cmp_lt_i32 s47, 0
	s_cbranch_scc1 .Lp4_win_pq1
	s_lshl_b32 s22, s16, 11
	s_lshl_b32 s23, s47, 6
	s_add_u32 s22, s22, s23
	s_mul_i32 s22, s22, 0x1240
	s_add_u32 s22, s22, s31
	s_mul_i32 s23, s18, 0x42000
	s_lshl_b32 s24, s47, 7
	s_add_u32 s23, s23, s24
	s_add_u32 s51, s53, s50
	s_mov_b32 m0, s51
	v_add_u32_e32 v211, s22, v201
	v_mov_b32_e32 v245, s1
	v_add_co_u32_e32 v244, vcc, s0, v211
	s_nop 1
	v_addc_co_u32_e32 v245, vcc, 0, v245, vcc
	global_load_lds_dwordx4 v[244:245], off
	s_add_u32 s51, s51, 1024
	s_mov_b32 m0, s51
	v_add_u32_e32 v212, s22, v202
	v_mov_b32_e32 v245, s1
	v_add_co_u32_e32 v244, vcc, s0, v212
	s_nop 1
	v_addc_co_u32_e32 v245, vcc, 0, v245, vcc
	global_load_lds_dwordx4 v[244:245], off
	s_add_u32 s51, s51, 7168
	s_mov_b32 m0, s51
	v_add_u32_e32 v213, s23, v203
	v_mov_b32_e32 v245, s43
	v_add_co_u32_e32 v244, vcc, s42, v213
	s_nop 1
	v_addc_co_u32_e32 v245, vcc, 0, v245, vcc
	global_load_lds_dwordx4 v[244:245], off
	s_add_u32 s51, s51, 1024
	s_mov_b32 m0, s51
	v_add_u32_e32 v214, s23, v204
	v_mov_b32_e32 v245, s43
	v_add_co_u32_e32 v244, vcc, s42, v214
	s_nop 1
	v_addc_co_u32_e32 v245, vcc, 0, v245, vcc
	global_load_lds_dwordx4 v[244:245], off

; DEVI f32x4 mfma16(bf16x8 a, bf16x8 b, f32x4 c) { return __builtin_amdgcn_mfma_f32_16x16x32_bf16(a, b, c, 0, 0, 0); }
; DEVI float fexp2(float x) { return __builtin_amdgcn_exp2f(x); }
; template <int DH, int NQ, int LDK, class MaskF>
; DEVI void attn_qk(const u16* sK, const bf16x8 (&qf)[NQ][DH / 32], f32x4 (&o)[NQ][DH / 16], float (&m)[NQ], float (&l)[NQ],
;                   float c2, int lane, MaskF valid, bf16x8 (&pb)[NQ][2]) {
;   const int col = lane & 15, quad = lane >> 4;
;   f32x4 s[NQ][4];
;   __builtin_amdgcn_s_setprio(1);
; #pragma unroll
;   for (int kt = 0; kt < 4; ++kt) {
; #pragma unroll
;     for (int qt = 0; qt < NQ; ++qt) s[qt][kt] = f32x4{0.f, 0.f, 0.f, 0.f};
; #pragma unroll
;     for (int ks = 0; ks < DH / 32; ++ks) {
;       const bf16x8 kf = *(const bf16x8*)(sK + (16 * kt + col) * LDK + 32 * ks + 8 * quad);
; #pragma unroll
;       for (int qt = 0; qt < NQ; ++qt) s[qt][kt] = mfma16(kf, qf[qt][ks], s[qt][kt]);
;     }
;   }
;   __builtin_amdgcn_s_setprio(0);
; #pragma unroll
;   for (int qt = 0; qt < NQ; ++qt) {
;     float mx = -1e30f;
; #pragma unroll
;     for (int kt = 0; kt < 4; ++kt)
; #pragma unroll
;       for (int r = 0; r < 4; ++r) {
;         const bool v = valid(qt, 16 * kt + 4 * quad + r);
;         const float sv = v ? s[qt][kt][r] : -1e30f;
;         s[qt][kt][r] = sv;
;         mx = fmaxf(mx, sv);
;       }
;     mx = fmaxf(mx, __shfl_xor(mx, 16));
;     mx = fmaxf(mx, __shfl_xor(mx, 32));
;     const float mn = fmaxf(m[qt], mx);
;     const float alpha = fexp2((m[qt] - mn) * c2);
; DEVI void phase_nsa(const Params& p, unsigned char* smem) {
;     ...
;       LOADKV_(kb, C_KW, p.vtw)
; #pragma unroll 1
;       while (kb >= 0) {
;         const int nkb = (kb < kbmax) ? kb + 1 : -1;
;         __syncthreads();
;         STOREKV_()
;         if (nkb >= 0) { LOADKV_(nkb, C_KW, p.vtw) }
;         __syncthreads();
;         attn_tile<64, 2, 72, 72>(sK, sVt, qf, o, m, l, c2, lane, [&](int qt, int kl) {
;           return (unsigned)(tq[qt] - (kb * 64 + kl)) < 512u;
;         });
.Lp4_win_nq3:
	s_lshl_b32 s30, s26, 6
	v_lshlrev_b32_e32 v217, 2, v198
	v_sub_u32_e32 v207, v186, v217
	v_lshlrev_b32_e32 v217, 2, v198
	v_sub_u32_e32 v208, v187, v217
	s_add_u32 s23, s30, 63
	s_cmp_le_u32 s23, s19
	s_cselect_b32 s24, 1, 0
	s_add_u32 s23, s30, 0x1e0
	s_cmp_ge_u32 s23, s19
	s_cselect_b32 s24, s24, 0
	s_cmp_eq_u32 s24, 0
	s_cbranch_scc1 .Lp4_win_masked
	v_add_u32_e32 v227, s46, v235
	v_add_u32_e32 v228, s46, v236
	v_add_u32_e32 v231, s46, v237
	v_add_u32_e32 v233, s46, v239
	v_add_u32_e32 v232, s46, v238
	v_add_u32_e32 v234, s46, v240
	ds_read_b128 v[112:115], v227
	ds_read_b128 v[116:119], v228
	ds_read_b128 v[120:123], v227 offset:2048
	ds_read_b128 v[124:127], v228 offset:2048
	ds_read_b128 v[128:131], v227 offset:4096
	ds_read_b128 v[132:135], v228 offset:4096
	ds_read_b128 v[136:139], v227 offset:6144
	ds_read_b128 v[140:143], v228 offset:6144
	s_waitcnt lgkmcnt(7)
	v_mfma_f32_16x16x32_bf16 v[80:83], v[112:115], v[0:3], 0
	v_mfma_f32_16x16x32_bf16 v[96:99], v[112:115], v[8:11], 0
	s_waitcnt lgkmcnt(6)
	v_mfma_f32_16x16x32_bf16 v[80:83], v[116:119], v[4:7], v[80:83]
	v_mfma_f32_16x16x32_bf16 v[96:99], v[116:119], v[12:15], v[96:99]
	s_waitcnt lgkmcnt(5)
	v_mfma_f32_16x16x32_bf16 v[84:87], v[120:123], v[0:3], 0
	v_mfma_f32_16x16x32_bf16 v[100:103], v[120:123], v[8:11], 0
	s_waitcnt lgkmcnt(4)
	v_mfma_f32_16x16x32_bf16 v[84:87], v[124:127], v[4:7], v[84:87]
	v_mfma_f32_16x16x32_bf16 v[100:103], v[124:127], v[12:15], v[100:103]
	s_waitcnt lgkmcnt(3)
	v_mfma_f32_16x16x32_bf16 v[88:91], v[128:131], v[0:3], 0
	v_mfma_f32_16x16x32_bf16 v[104:107], v[128:131], v[8:11], 0
	s_waitcnt lgkmcnt(2)
	v_mfma_f32_16x16x32_bf16 v[88:91], v[132:135], v[4:7], v[88:91]
	v_mfma_f32_16x16x32_bf16 v[104:107], v[132:135], v[12:15], v[104:107]
	s_waitcnt lgkmcnt(1)
	v_mfma_f32_16x16x32_bf16 v[92:95], v[136:139], v[0:3], 0
	v_mfma_f32_16x16x32_bf16 v[108:111], v[136:139], v[8:11], 0
	s_waitcnt lgkmcnt(0)
	v_mfma_f32_16x16x32_bf16 v[92:95], v[140:143], v[4:7], v[92:95]
	v_mfma_f32_16x16x32_bf16 v[108:111], v[140:143], v[12:15], v[108:111]
	ds_read_b64 v[112:113], v231 offset:0
	ds_read_b64 v[114:115], v233 offset:0
	ds_read_b64 v[116:117], v232 offset:0
	ds_read_b64 v[118:119], v234 offset:0
	ds_read_b64 v[120:121], v231 offset:2048
	ds_read_b64 v[122:123], v233 offset:2048
	ds_read_b64 v[124:125], v232 offset:2048
	ds_read_b64 v[126:127], v234 offset:2048
	s_nop 3
	v_max3_f32 v215, v80, v81, v82
	v_max3_f32 v215, v215, v83, v84
	v_max3_f32 v215, v215, v85, v86
	v_max3_f32 v215, v215, v87, v88
	v_max3_f32 v215, v215, v89, v90
	v_max3_f32 v215, v215, v91, v92
	v_max3_f32 v215, v215, v93, v94
	v_max_f32_e32 v215, v95, v215
	ds_bpermute_b32 v216, v195, v215
	s_waitcnt lgkmcnt(0)
	v_max_f32_e32 v215, v216, v215
	v_mov_b32_e32 v216, v215
	v_mov_b32_e32 v217, v215
	s_nop 1
	v_permlane32_swap_b32_e32 v216, v217
	v_max_f32_e32 v215, v216, v217
	v_max_f32_e32 v218, v182, v215
	v_sub_f32_e32 v219, v182, v218
	v_mul_f32_e32 v219, v200, v219
	v_exp_f32_e32 v219, v219
	v_mov_b32_e32 v182, v218
	v_max_f32_e32 v220, 0xe0ad78ec, v218
	v_mul_f32_e32 v220, 0xbe38aa3b, v220
	v_fma_f32 v80, v80, v200, v220
	v_exp_f32_e32 v80, v80
	v_fma_f32 v81, v81, v200, v220
	v_exp_f32_e32 v81, v81
	v_fma_f32 v82, v82, v200, v220
	v_exp_f32_e32 v82, v82
	v_fma_f32 v83, v83, v200, v220
	v_exp_f32_e32 v83, v83
	v_fma_f32 v84, v84, v200, v220
	v_exp_f32_e32 v84, v84
	v_fma_f32 v85, v85, v200, v220
	v_exp_f32_e32 v85, v85
	v_fma_f32 v86, v86, v200, v220
	v_exp_f32_e32 v86, v86
	v_fma_f32 v87, v87, v200, v220
	v_exp_f32_e32 v87, v87
	v_fma_f32 v88, v88, v200, v220
	v_exp_f32_e32 v88, v88
	v_fma_f32 v89, v89, v200, v220
	v_exp_f32_e32 v89, v89
	v_fma_f32 v90, v90, v200, v220
	v_exp_f32_e32 v90, v90
	v_fma_f32 v91, v91, v200, v220
	v_exp_f32_e32 v91, v91
	v_fma_f32 v92, v92, v200, v220
	v_exp_f32_e32 v92, v92
	v_fma_f32 v93, v93, v200, v220
	v_exp_f32_e32 v93, v93
	v_fma_f32 v94, v94, v200, v220
	v_exp_f32_e32 v94, v94
	v_fma_f32 v95, v95, v200, v220
	v_exp_f32_e32 v95, v95
	s_nop 0
	v_add_f32_e32 v221, v80, v81
	v_add_f32_e32 v221, v82, v221
	v_add_f32_e32 v221, v83, v221
	v_add_f32_e32 v221, v84, v221
	v_add_f32_e32 v221, v85, v221
	v_add_f32_e32 v221, v86, v221
	v_add_f32_e32 v221, v87, v221
	v_add_f32_e32 v221, v88, v221
	v_add_f32_e32 v221, v89, v221
	v_add_f32_e32 v221, v90, v221
	v_add_f32_e32 v221, v91, v221
	v_add_f32_e32 v221, v92, v221
	v_add_f32_e32 v221, v93, v221
	v_add_f32_e32 v221, v94, v221
	v_add_f32_e32 v221, v95, v221
	v_fma_f32 v184, v184, v219, v221
	v_mul_f32_e32 v16, v219, v16
	v_mul_f32_e32 v17, v219, v17
	v_mul_f32_e32 v18, v219, v18
	v_mul_f32_e32 v19, v219, v19
	v_mul_f32_e32 v20, v219, v20
	v_mul_f32_e32 v21, v219, v21
	v_mul_f32_e32 v22, v219, v22
	v_mul_f32_e32 v23, v219, v23
	v_mul_f32_e32 v24, v219, v24
	v_mul_f32_e32 v25, v219, v25
	v_mul_f32_e32 v26, v219, v26
	v_mul_f32_e32 v27, v219, v27
	v_mul_f32_e32 v28, v219, v28
	v_mul_f32_e32 v29, v219, v29
	v_mul_f32_e32 v30, v219, v30
	v_mul_f32_e32 v31, v219, v31
	v_cvt_pk_bf16_f32 v144, v80, v81
	v_cvt_pk_bf16_f32 v145, v82, v83
	v_cvt_pk_bf16_f32 v146, v84, v85
	v_cvt_pk_bf16_f32 v147, v86, v87
	v_cvt_pk_bf16_f32 v148, v88, v89
	v_cvt_pk_bf16_f32 v149, v90, v91
	v_cvt_pk_bf16_f32 v150, v92, v93
	v_cvt_pk_bf16_f32 v151, v94, v95
	v_max3_f32 v215, v96, v97, v98
	v_max3_f32 v215, v215, v99, v100
	v_max3_f32 v215, v215, v101, v102
	v_max3_f32 v215, v215, v103, v104
	v_max3_f32 v215, v215, v105, v106
	v_max3_f32 v215, v215, v107, v108
	v_max3_f32 v215, v215, v109, v110
	v_max_f32_e32 v215, v111, v215
	ds_bpermute_b32 v216, v195, v215
	s_waitcnt lgkmcnt(0)
; DEVI unsigned pack2(float a, float b) { return (unsigned)f2bf(a) | ((unsigned)f2bf(b) << 16); }
; DEVI f32x4 mfma16(bf16x8 a, bf16x8 b, f32x4 c) { return __builtin_amdgcn_mfma_f32_16x16x32_bf16(a, b, c, 0, 0, 0); }
; DEVI float fexp2(float x) { return __builtin_amdgcn_exp2f(x); }
; template <int DH, int NQ, int LDK, class MaskF>
; DEVI void attn_qk(const u16* sK, const bf16x8 (&qf)[NQ][DH / 32], f32x4 (&o)[NQ][DH / 16], float (&m)[NQ], float (&l)[NQ],
;                   float c2, int lane, MaskF valid, bf16x8 (&pb)[NQ][2]) {
;     ...
;     mx = fmaxf(mx, __shfl_xor(mx, 16));
;     mx = fmaxf(mx, __shfl_xor(mx, 32));
;     const float mn = fmaxf(m[qt], mx);
;     const float alpha = fexp2((m[qt] - mn) * c2);
;     m[qt] = mn;
;     const float mc = fmaxf(mn, -1e20f) * c2;
;     float ps = 0.f;
; #pragma unroll
;     for (int kt = 0; kt < 4; ++kt)
; #pragma unroll
;       for (int r = 0; r < 4; ++r) {
;         const float pv = fexp2(__builtin_fmaf(s[qt][kt][r], c2, -mc));
;         ps += pv;
;         s[qt][kt][r] = pv;
;       }
;     l[qt] = l[qt] * alpha + ps;
; #pragma unroll
;     for (int dt = 0; dt < DH / 16; ++dt) o[qt][dt] *= alpha;
; #pragma unroll
;     for (int kk = 0; kk < 2; ++kk) {
;       union { bf16x8 v; unsigned u[4]; } cv;
;       cv.u[0] = pack2(s[qt][2 * kk][0], s[qt][2 * kk][1]);
;       cv.u[1] = pack2(s[qt][2 * kk][2], s[qt][2 * kk][3]);
;       cv.u[2] = pack2(s[qt][2 * kk + 1][0], s[qt][2 * kk + 1][1]);
;       cv.u[3] = pack2(s[qt][2 * kk + 1][2], s[qt][2 * kk + 1][3]);
;       pb[qt][kk] = cv.v;
;     }
;   }
; }
; template <int DH, int NQ, int LDV>
; DEVI void attn_pv(const u16* sVt, const bf16x8 (&pb)[NQ][2], f32x4 (&o)[NQ][DH / 16], int lane) {
;   const int col = lane & 15, quad = lane >> 4;
;   __builtin_amdgcn_s_setprio(1);
; #pragma unroll
;   for (int dt = 0; dt < DH / 16; ++dt) {
; #pragma unroll
;     for (int kk = 0; kk < 2; ++kk) {
;       union { bf16x8 v; uint2 h[2]; } cv;
;       cv.h[0] = *(const uint2*)(sVt + (16 * dt + col) * LDV + 32 * kk + 4 * quad);
;       cv.h[1] = *(const uint2*)(sVt + (16 * dt + col) * LDV + 32 * kk + 16 + 4 * quad);
; #pragma unroll
;       for (int qt = 0; qt < NQ; ++qt) o[qt][dt] = mfma16(cv.v, pb[qt][kk], o[qt][dt]);
;     }
;   }
;   __builtin_amdgcn_s_setprio(0);
	v_max_f32_e32 v215, v216, v215
	v_mov_b32_e32 v216, v215
	v_mov_b32_e32 v217, v215
	s_nop 1
	v_permlane32_swap_b32_e32 v216, v217
	v_max_f32_e32 v215, v216, v217
	v_max_f32_e32 v218, v183, v215
	v_sub_f32_e32 v219, v183, v218
	v_mul_f32_e32 v219, v200, v219
	v_exp_f32_e32 v219, v219
	v_mov_b32_e32 v183, v218
	v_max_f32_e32 v220, 0xe0ad78ec, v218
	v_mul_f32_e32 v220, 0xbe38aa3b, v220
	v_fma_f32 v96, v96, v200, v220
	v_exp_f32_e32 v96, v96
	v_fma_f32 v97, v97, v200, v220
	v_exp_f32_e32 v97, v97
	v_fma_f32 v98, v98, v200, v220
	v_exp_f32_e32 v98, v98
	v_fma_f32 v99, v99, v200, v220
	v_exp_f32_e32 v99, v99
	v_fma_f32 v100, v100, v200, v220
	v_exp_f32_e32 v100, v100
	v_fma_f32 v101, v101, v200, v220
	v_exp_f32_e32 v101, v101
	v_fma_f32 v102, v102, v200, v220
	v_exp_f32_e32 v102, v102
	v_fma_f32 v103, v103, v200, v220
	v_exp_f32_e32 v103, v103
	v_fma_f32 v104, v104, v200, v220
	v_exp_f32_e32 v104, v104
	v_fma_f32 v105, v105, v200, v220
	v_exp_f32_e32 v105, v105
	v_fma_f32 v106, v106, v200, v220
	v_exp_f32_e32 v106, v106
	v_fma_f32 v107, v107, v200, v220
	v_exp_f32_e32 v107, v107
	v_fma_f32 v108, v108, v200, v220
	v_exp_f32_e32 v108, v108
	v_fma_f32 v109, v109, v200, v220
	v_exp_f32_e32 v109, v109
	v_fma_f32 v110, v110, v200, v220
	v_exp_f32_e32 v110, v110
	v_fma_f32 v111, v111, v200, v220
	v_exp_f32_e32 v111, v111
	s_nop 0
	v_add_f32_e32 v221, v96, v97
	v_add_f32_e32 v221, v98, v221
	v_add_f32_e32 v221, v99, v221
	v_add_f32_e32 v221, v100, v221
	v_add_f32_e32 v221, v101, v221
	v_add_f32_e32 v221, v102, v221
	v_add_f32_e32 v221, v103, v221
	v_add_f32_e32 v221, v104, v221
	v_add_f32_e32 v221, v105, v221
	v_add_f32_e32 v221, v106, v221
	v_add_f32_e32 v221, v107, v221
	v_add_f32_e32 v221, v108, v221
	v_add_f32_e32 v221, v109, v221
	v_add_f32_e32 v221, v110, v221
	v_add_f32_e32 v221, v111, v221
	v_fma_f32 v185, v185, v219, v221
	v_mul_f32_e32 v32, v219, v32
	v_mul_f32_e32 v33, v219, v33
	v_mul_f32_e32 v34, v219, v34
	v_mul_f32_e32 v35, v219, v35
	v_mul_f32_e32 v36, v219, v36
	v_mul_f32_e32 v37, v219, v37
	v_mul_f32_e32 v38, v219, v38
	v_mul_f32_e32 v39, v219, v39
	v_mul_f32_e32 v40, v219, v40
	v_mul_f32_e32 v41, v219, v41
	v_mul_f32_e32 v42, v219, v42
	v_mul_f32_e32 v43, v219, v43
	v_mul_f32_e32 v44, v219, v44
	v_mul_f32_e32 v45, v219, v45
	v_mul_f32_e32 v46, v219, v46
	v_mul_f32_e32 v47, v219, v47
	v_cvt_pk_bf16_f32 v152, v96, v97
	v_cvt_pk_bf16_f32 v153, v98, v99
	v_cvt_pk_bf16_f32 v154, v100, v101
	v_cvt_pk_bf16_f32 v155, v102, v103
	v_cvt_pk_bf16_f32 v156, v104, v105
	v_cvt_pk_bf16_f32 v157, v106, v107
	v_cvt_pk_bf16_f32 v158, v108, v109
	v_cvt_pk_bf16_f32 v159, v110, v111
	ds_read_b64 v[128:129], v231 offset:4096
	ds_read_b64 v[130:131], v233 offset:4096
	ds_read_b64 v[132:133], v232 offset:4096
	ds_read_b64 v[134:135], v234 offset:4096
	ds_read_b64 v[136:137], v231 offset:6144
	ds_read_b64 v[138:139], v233 offset:6144
	ds_read_b64 v[140:141], v232 offset:6144
	ds_read_b64 v[142:143], v234 offset:6144
	s_waitcnt lgkmcnt(8)
	v_mfma_f32_16x16x32_bf16 v[16:19], v[112:115], v[144:147], v[16:19]
	v_mfma_f32_16x16x32_bf16 v[32:35], v[112:115], v[152:155], v[32:35]
	v_mfma_f32_16x16x32_bf16 v[16:19], v[116:119], v[148:151], v[16:19]
	v_mfma_f32_16x16x32_bf16 v[32:35], v[116:119], v[156:159], v[32:35]
	v_mfma_f32_16x16x32_bf16 v[20:23], v[120:123], v[144:147], v[20:23]
	v_mfma_f32_16x16x32_bf16 v[36:39], v[120:123], v[152:155], v[36:39]
	v_mfma_f32_16x16x32_bf16 v[20:23], v[124:127], v[148:151], v[20:23]
	v_mfma_f32_16x16x32_bf16 v[36:39], v[124:127], v[156:159], v[36:39]
	s_waitcnt lgkmcnt(0)
	v_mfma_f32_16x16x32_bf16 v[24:27], v[128:131], v[144:147], v[24:27]
	v_mfma_f32_16x16x32_bf16 v[40:43], v[128:131], v[152:155], v[40:43]
	v_mfma_f32_16x16x32_bf16 v[24:27], v[132:135], v[148:151], v[24:27]
	v_mfma_f32_16x16x32_bf16 v[40:43], v[132:135], v[156:159], v[40:43]
	v_mfma_f32_16x16x32_bf16 v[28:31], v[136:139], v[144:147], v[28:31]
	v_mfma_f32_16x16x32_bf16 v[44:47], v[136:139], v[152:155], v[44:47]
	v_mfma_f32_16x16x32_bf16 v[28:31], v[140:143], v[148:151], v[28:31]
	v_mfma_f32_16x16x32_bf16 v[44:47], v[140:143], v[156:159], v[44:47]
	s_branch .Lp4_win_next

; DEVI void phase_nsa(const Params& p, unsigned char* smem) {
;     ...
;       while (kb >= 0) {
;         const int nkb = (kb < kbmax) ? kb + 1 : -1;
;         __syncthreads();
;         STOREKV_()
;         if (nkb >= 0) { LOADKV_(nkb, C_KW, p.vtw) }
;         __syncthreads();
;         attn_tile<64, 2, 72, 72>(sK, sVt, qf, o, m, l, c2, lane, [&](int qt, int kl) {
;           return (unsigned)(tq[qt] - (kb * 64 + kl)) < 512u;
;         });
;         kb = nkb;
;       }
.Lp4_win_next:
	s_mov_b32 s26, s47
	s_mov_b32 s47, s48
	s_mov_b32 s48, s49
	s_add_u32 s46, s46, 0x4000
	s_and_b32 s46, s46, 0xffff
	s_mov_b32 s49, s52
	s_add_u32 s22, s52, 1
	s_cmp_lt_i32 s52, s20
	s_cselect_b32 s22, s22, -1
	s_cmp_lt_i32 s52, 0
	s_cselect_b32 s52, -1, s22
	s_cmp_lt_i32 s26, 0
	s_cbranch_scc0 .Lp4_win_loop

; DEVI void phase_nsa(const Params& p, unsigned char* smem) {
;     ...
;   }
; }
.Lp4_done:
	s_waitcnt vmcnt(0)
	v_readlane_b32 s46, v247, 32
	v_readlane_b32 s47, v247, 33
	v_readlane_b32 s48, v247, 34
	v_readlane_b32 s49, v247, 35
	v_readlane_b32 s50, v247, 36
	v_readlane_b32 s51, v247, 37
	v_readlane_b32 s52, v247, 38
	v_readlane_b32 s53, v247, 39
